# GEMM k-loop: LDS-DMA issue spread 3/2/2/1 over the four MFMA groups of a k-tile
# speedup vs baseline: 1.0328x; 1.0031x over previous
; template <class Epi>
; DI void gemm_phase(const u16* __restrict__ A, const u16* __restrict__ B, int mtiles, int ntiles, char* lds, const Epi& epi) {
;     ...
;     for (;;) {
;         int tid = threadIdx.x; asm volatile("" : "+v"(tid));
;         const int lane = tid & 63, wave = __builtin_amdgcn_readfirstlane(tid >> 6); const int wn = wave >> 1, wm = wave & 1; const int r = lane & 31, h = lane >> 5;
;         f32x16 acc[2][2];
; #pragma unroll
;         for (int a = 0; a < 2; ++a)
; #pragma unroll
;             for (int b = 0; b < 2; ++b)
; #pragma unroll
;                 for (int e = 0; e < 16; ++e) acc[a][b][e] = 0.f;
;         unsigned soff[4];
; #pragma unroll
;         for (int i = 0; i < 4; ++i) { const int row = 8 * (i * 4 + wave) + (lane >> 3); const int ch = (lane & 7) ^ ((row >> 1) & 7); soff[i] = (unsigned)(row * 1024 + ch * 8); }
;         const u16* ga = A + (size_t)m0 * 1024; const u16* gb = B + (size_t)n0 * 1024;
;         __syncthreads();
;         for (int kt = 0; kt < 16; ++kt) {
;             if (kt + 1 < 16) GSTAGE((kt + 1) & 1, kt + 1, ga, gb);
;             const char* sa = lds + (kt & 1) * 32768; const char* sb = sa + 16384;
; #pragma unroll
;             for (int ks = 0; ks < 4; ++ks) {
;                 bf16x8 fw[2], fx[2];
; #pragma unroll
;                 for (int ct = 0; ct < 2; ++ct) fw[ct] = *(const bf16x8*)(sb + swz(wn * 64 + ct * 32 + r, 2 * ks + h));
; #pragma unroll
;                 for (int tt = 0; tt < 2; ++tt) fx[tt] = *(const bf16x8*)(sa + swz(wm * 64 + tt * 32 + r, 2 * ks + h));
; #pragma unroll
;                 for (int ct = 0; ct < 2; ++ct)
; #pragma unroll
;                     for (int tt = 0; tt < 2; ++tt) acc[ct][tt] = __builtin_amdgcn_mfma_f32_32x32x16_bf16(fw[ct], fx[tt], acc[ct][tt], 0, 0, 0);
;             }
.LBB0_97:
	v_mov_b32_e32 v18, v0
	s_ashr_i32 s83, s82, 31
	v_readfirstlane_b32 s1, v18
	s_ashr_i32 s7, s1, 6
	s_ashr_i32 s4, s1, 7
	s_and_b32 s6, s7, 1
	v_bfe_u32 v2, v18, 3, 3
	s_lshl_b64 s[38:39], s[82:83], 11
	v_lshl_or_b32 v2, s7, 3, v2
	s_add_u32 s38, s54, s38
	v_lshrrev_b32_e32 v3, 1, v2
	s_addc_u32 s39, s55, s39
	s_ashr_i32 s1, s0, 31
	v_xor_b32_e32 v3, v3, v18
	s_lshl_b64 s[50:51], s[0:1], 11
	v_readlane_b32 s1, v236, 9
	v_lshlrev_b32_e32 v2, 10, v2
	v_lshlrev_b32_e32 v3, 3, v3
	s_add_u32 s50, s1, s50
	v_readlane_b32 s1, v236, 11
	v_and_or_b32 v74, v3, 56, v2
	s_addc_u32 s51, s1, s51
	s_lshl_b32 s1, s7, 10
	v_lshlrev_b64 v[66:67], 1, v[74:75]
	s_add_i32 s1, s1, 0
	v_add_u32_e32 v2, 0x8000, v74
	v_bfe_u32 v93, v18, 5, 1
	v_lshrrev_b32_e32 v8, 1, v18
	v_mov_b32_e32 v3, v75
	v_lshl_add_u64 v[76:77], s[38:39], 0, v[66:67]
	s_add_i32 s86, s1, 0x8000
	v_bitop3_b32 v10, v93, v8, 7 bitop3:0x78
	v_lshl_add_u64 v[8:9], v[76:77], 0, s[8:9]
	s_mov_b32 m0, s86
	v_lshl_add_u64 v[78:79], s[50:51], 0, v[66:67]
	s_add_i32 s87, s1, 0xc000
	v_lshlrev_b64 v[68:69], 1, v[2:3]
	v_add_u32_e32 v4, 0x10000, v74
	s_waitcnt vmcnt(0) lgkmcnt(0)
	s_barrier
	v_mov_b32_e32 v5, v75
	global_load_lds_dwordx4 v[8:9], off
	v_lshl_add_u64 v[8:9], v[78:79], 0, s[8:9]
	s_mov_b32 m0, s87
	v_lshl_add_u64 v[80:81], s[38:39], 0, v[68:69]
	s_add_i32 s88, s1, 0x9000
	global_load_lds_dwordx4 v[8:9], off
	v_lshl_add_u64 v[2:3], v[80:81], 0, s[8:9]
	s_mov_b32 m0, s88
	v_lshl_add_u64 v[82:83], s[50:51], 0, v[68:69]
	s_add_i32 s89, s1, 0xd000
	v_lshlrev_b64 v[70:71], 1, v[4:5]
	v_add_u32_e32 v6, 0x18000, v74
	v_mov_b32_e32 v7, v75
	global_load_lds_dwordx4 v[2:3], off
	v_lshl_add_u64 v[2:3], v[82:83], 0, s[8:9]
	s_mov_b32 m0, s89
	v_lshl_add_u64 v[84:85], s[38:39], 0, v[70:71]
	s_add_i32 s91, s1, 0xa000
	global_load_lds_dwordx4 v[2:3], off
	v_lshl_add_u64 v[2:3], v[84:85], 0, s[8:9]
	s_mov_b32 m0, s91
	v_lshl_add_u64 v[86:87], s[50:51], 0, v[70:71]
	s_add_i32 s92, s1, 0xe000
	v_lshlrev_b64 v[72:73], 1, v[6:7]
	global_load_lds_dwordx4 v[2:3], off
	v_lshl_add_u64 v[2:3], v[86:87], 0, s[8:9]
	s_mov_b32 m0, s92
	v_lshl_add_u64 v[88:89], s[38:39], 0, v[72:73]
	s_add_i32 s93, s1, 0xb000
	v_and_b32_e32 v94, 31, v18
	global_load_lds_dwordx4 v[2:3], off
	v_lshl_add_u64 v[2:3], v[88:89], 0, s[8:9]
	s_mov_b32 m0, s93
	v_lshl_add_u64 v[90:91], s[50:51], 0, v[72:73]
	s_add_i32 s94, s1, 0xf000
	s_lshl_b32 s7, s4, 13
	v_lshlrev_b32_e32 v116, 7, v94
	global_load_lds_dwordx4 v[2:3], off
	v_lshl_add_u64 v[2:3], v[90:91], 0, s[8:9]
	s_mov_b32 m0, s94
	v_lshl_add_u32 v6, v10, 4, 0
	global_load_lds_dwordx4 v[2:3], off
	v_add3_u32 v74, v6, s7, v116
	ds_read_b128 v[2:5], v74 offset:16384
	s_lshl_b32 s38, s6, 13
	v_add3_u32 v96, v6, s38, v116
	v_bfe_u32 v117, v18, 1, 3
	ds_read_b128 v[6:9], v96
	ds_read_b128 v[10:13], v96 offset:4096
	ds_read_b128 v[14:17], v74 offset:20480
	v_bitop3_b32 v18, v93, v117, 2 bitop3:0x36
	v_lshl_add_u32 v18, v18, 4, 0
	v_add3_u32 v95, v18, s7, v116
	ds_read_b128 v[50:53], v95 offset:16384
	s_waitcnt lgkmcnt(0)
	v_mfma_f32_32x32x16_bf16 v[34:49], v[2:5], v[6:9], 0
	v_add3_u32 v97, v18, s38, v116
	ds_read_b128 v[98:101], v97
	ds_read_b128 v[102:105], v97 offset:4096
	ds_read_b128 v[106:109], v95 offset:20480
	s_mov_b32 m0, s1
	s_add_i32 s39, s1, 0x5000
	s_add_i32 s50, s1, 0x2000
	s_add_i32 s51, s1, 0x6000
	s_add_i32 s83, s1, 0x3000
	v_mfma_f32_32x32x16_bf16 v[18:33], v[2:5], v[10:13], 0
	s_add_i32 s90, s1, 0x7000
	s_add_i32 s33, s33, s95
	s_waitcnt lgkmcnt(0)
	v_mfma_f32_32x32x16_bf16 v[34:49], v[50:53], v[98:101], v[34:49]
	v_mfma_f32_32x32x16_bf16 v[18:33], v[50:53], v[102:105], v[18:33]
	v_mfma_f32_32x32x16_bf16 v[50:65], v[14:17], v[6:9], 0
	v_mfma_f32_32x32x16_bf16 v[2:17], v[14:17], v[10:13], 0
	v_mfma_f32_32x32x16_bf16 v[50:65], v[106:109], v[98:101], v[50:65]
	v_bitop3_b32 v98, v93, v117, 4 bitop3:0x36
	v_lshl_add_u32 v99, v98, 4, 0
	v_add3_u32 v98, v99, s7, v116
	v_add3_u32 v99, v99, s38, v116
	v_mfma_f32_32x32x16_bf16 v[2:17], v[106:109], v[102:105], v[2:17]
	ds_read_b128 v[100:103], v98 offset:16384
	ds_read_b128 v[104:107], v99
	ds_read_b128 v[108:111], v99 offset:4096
	ds_read_b128 v[112:115], v98 offset:20480
	s_waitcnt lgkmcnt(0)
	v_mfma_f32_32x32x16_bf16 v[34:49], v[100:103], v[104:107], v[34:49]
	v_mfma_f32_32x32x16_bf16 v[18:33], v[100:103], v[108:111], v[18:33]
	v_bitop3_b32 v100, v93, v117, 6 bitop3:0x36
	v_lshl_add_u32 v101, v100, 4, 0
	v_add3_u32 v100, v101, s7, v116
	v_add3_u32 v101, v101, s38, v116
	s_add_i32 s7, s1, 0x4000
	s_add_i32 s38, s1, 0x1000
	s_cmpk_gt_i32 s33, 0x1103
	v_mfma_f32_32x32x16_bf16 v[50:65], v[112:115], v[104:107], v[50:65]
	v_mfma_f32_32x32x16_bf16 v[2:17], v[112:115], v[108:111], v[2:17]
	ds_read_b128 v[238:241], v100 offset:16384
	ds_read_b128 v[242:245], v101
	ds_read_b128 v[246:249], v101 offset:4096
	ds_read_b128 v[250:253], v100 offset:20480
	s_waitcnt vmcnt(0) lgkmcnt(0)
	s_barrier
; template <class Epi>
; DI void gemm_phase(const u16* __restrict__ A, const u16* __restrict__ B, int mtiles, int ntiles, char* lds, const Epi& epi) {
;     ...
;         for (int kt = 0; kt < 16; ++kt) {
;             if (kt + 1 < 16) GSTAGE((kt + 1) & 1, kt + 1, ga, gb);
;             const char* sa = lds + (kt & 1) * 32768; const char* sb = sa + 16384;
; #pragma unroll
;             for (int ks = 0; ks < 4; ++ks) {
;                 bf16x8 fw[2], fx[2];
; #pragma unroll
;                 for (int ct = 0; ct < 2; ++ct) fw[ct] = *(const bf16x8*)(sb + swz(wn * 64 + ct * 32 + r, 2 * ks + h));
; #pragma unroll
;                 for (int tt = 0; tt < 2; ++tt) fx[tt] = *(const bf16x8*)(sa + swz(wm * 64 + tt * 32 + r, 2 * ks + h));
; #pragma unroll
;                 for (int ct = 0; ct < 2; ++ct)
; #pragma unroll
;                     for (int tt = 0; tt < 2; ++tt) acc[ct][tt] = __builtin_amdgcn_mfma_f32_32x32x16_bf16(fw[ct], fx[tt], acc[ct][tt], 0, 0, 0);
;             }
;             __syncthreads();
;         }
	ds_read_b128 v[102:105], v74 offset:49152
	ds_read_b128 v[106:109], v96 offset:32768
	ds_read_b128 v[110:113], v96 offset:36864
	ds_read_b128 v[114:117], v74 offset:53248
	v_mfma_f32_32x32x16_bf16 v[34:49], v[238:241], v[242:245], v[34:49]
	v_mfma_f32_32x32x16_bf16 v[18:33], v[238:241], v[246:249], v[18:33]
	v_lshl_add_u64 v[254:255], v[76:77], 0, s[10:11]
	global_load_lds_dwordx4 v[254:255], off
	v_lshl_add_u64 v[254:255], v[78:79], 0, s[10:11]
	s_mov_b32 m0, s7
	s_nop 0
	global_load_lds_dwordx4 v[254:255], off
	v_mfma_f32_32x32x16_bf16 v[50:65], v[250:253], v[242:245], v[50:65]
	v_lshl_add_u64 v[254:255], v[80:81], 0, s[10:11]
	s_mov_b32 m0, s38
	s_nop 0
	global_load_lds_dwordx4 v[254:255], off
	v_mfma_f32_32x32x16_bf16 v[2:17], v[250:253], v[246:249], v[2:17]
	s_waitcnt lgkmcnt(0)
	ds_read_b128 v[238:241], v95 offset:49152
	ds_read_b128 v[242:245], v97 offset:32768
	ds_read_b128 v[246:249], v97 offset:36864
	ds_read_b128 v[250:253], v95 offset:53248
	v_mfma_f32_32x32x16_bf16 v[34:49], v[102:105], v[106:109], v[34:49]
	v_lshl_add_u64 v[254:255], v[82:83], 0, s[10:11]
	s_mov_b32 m0, s39
	s_nop 0
	global_load_lds_dwordx4 v[254:255], off
	v_mfma_f32_32x32x16_bf16 v[18:33], v[102:105], v[110:113], v[18:33]
	v_lshl_add_u64 v[254:255], v[84:85], 0, s[10:11]
	s_mov_b32 m0, s50
	s_nop 0
	global_load_lds_dwordx4 v[254:255], off
	v_mfma_f32_32x32x16_bf16 v[50:65], v[114:117], v[106:109], v[50:65]
	v_mfma_f32_32x32x16_bf16 v[2:17], v[114:117], v[110:113], v[2:17]
	s_waitcnt lgkmcnt(0)
	ds_read_b128 v[102:105], v98 offset:49152
	ds_read_b128 v[106:109], v99 offset:32768
	ds_read_b128 v[110:113], v99 offset:36864
	ds_read_b128 v[114:117], v98 offset:53248
	v_mfma_f32_32x32x16_bf16 v[34:49], v[238:241], v[242:245], v[34:49]
	v_lshl_add_u64 v[254:255], v[86:87], 0, s[10:11]
	s_mov_b32 m0, s51
	s_nop 0
	global_load_lds_dwordx4 v[254:255], off
	v_mfma_f32_32x32x16_bf16 v[18:33], v[238:241], v[246:249], v[18:33]
	v_lshl_add_u64 v[254:255], v[88:89], 0, s[10:11]
	s_mov_b32 m0, s83
	s_nop 0
	global_load_lds_dwordx4 v[254:255], off
	v_mfma_f32_32x32x16_bf16 v[50:65], v[250:253], v[242:245], v[50:65]
	v_mfma_f32_32x32x16_bf16 v[2:17], v[250:253], v[246:249], v[2:17]
	s_waitcnt lgkmcnt(0)
	ds_read_b128 v[238:241], v100 offset:49152
	ds_read_b128 v[242:245], v101 offset:32768
	ds_read_b128 v[246:249], v101 offset:36864
	ds_read_b128 v[250:253], v100 offset:53248
	v_mfma_f32_32x32x16_bf16 v[34:49], v[102:105], v[106:109], v[34:49]
	v_lshl_add_u64 v[254:255], v[90:91], 0, s[10:11]
	s_mov_b32 m0, s90
	s_nop 0
	global_load_lds_dwordx4 v[254:255], off
	v_mfma_f32_32x32x16_bf16 v[18:33], v[102:105], v[110:113], v[18:33]
	v_mfma_f32_32x32x16_bf16 v[50:65], v[114:117], v[106:109], v[50:65]
	v_mfma_f32_32x32x16_bf16 v[2:17], v[114:117], v[110:113], v[2:17]
	s_mov_b32 m0, s86
	s_waitcnt vmcnt(0) lgkmcnt(0)
	s_barrier
	ds_read_b128 v[102:105], v74 offset:16384
	ds_read_b128 v[106:109], v96
	ds_read_b128 v[110:113], v96 offset:4096
	ds_read_b128 v[114:117], v74 offset:20480
	v_mfma_f32_32x32x16_bf16 v[34:49], v[238:241], v[242:245], v[34:49]
	v_mfma_f32_32x32x16_bf16 v[18:33], v[238:241], v[246:249], v[18:33]
	v_lshl_add_u64 v[254:255], v[76:77], 0, s[12:13]
	global_load_lds_dwordx4 v[254:255], off
	v_lshl_add_u64 v[254:255], v[78:79], 0, s[12:13]
	s_mov_b32 m0, s87
	s_nop 0
	global_load_lds_dwordx4 v[254:255], off
	v_mfma_f32_32x32x16_bf16 v[50:65], v[250:253], v[242:245], v[50:65]
	v_lshl_add_u64 v[254:255], v[80:81], 0, s[12:13]
	s_mov_b32 m0, s88
	s_nop 0
	global_load_lds_dwordx4 v[254:255], off
	v_mfma_f32_32x32x16_bf16 v[2:17], v[250:253], v[246:249], v[2:17]
	s_waitcnt lgkmcnt(0)
	ds_read_b128 v[238:241], v95 offset:16384
	ds_read_b128 v[242:245], v97
	ds_read_b128 v[246:249], v97 offset:4096
	ds_read_b128 v[250:253], v95 offset:20480
	v_mfma_f32_32x32x16_bf16 v[34:49], v[102:105], v[106:109], v[34:49]
	v_lshl_add_u64 v[254:255], v[82:83], 0, s[12:13]
	s_mov_b32 m0, s89
	s_nop 0
	global_load_lds_dwordx4 v[254:255], off
	v_mfma_f32_32x32x16_bf16 v[18:33], v[102:105], v[110:113], v[18:33]
	v_lshl_add_u64 v[254:255], v[84:85], 0, s[12:13]
	s_mov_b32 m0, s91
	s_nop 0
	global_load_lds_dwordx4 v[254:255], off
	v_mfma_f32_32x32x16_bf16 v[50:65], v[114:117], v[106:109], v[50:65]
	v_mfma_f32_32x32x16_bf16 v[2:17], v[114:117], v[110:113], v[2:17]
	s_waitcnt lgkmcnt(0)
	ds_read_b128 v[102:105], v98 offset:16384
	ds_read_b128 v[106:109], v99
	ds_read_b128 v[110:113], v99 offset:4096
	ds_read_b128 v[114:117], v98 offset:20480
	v_mfma_f32_32x32x16_bf16 v[34:49], v[238:241], v[242:245], v[34:49]
	v_lshl_add_u64 v[254:255], v[86:87], 0, s[12:13]
	s_mov_b32 m0, s92
	s_nop 0
	global_load_lds_dwordx4 v[254:255], off
	v_mfma_f32_32x32x16_bf16 v[18:33], v[238:241], v[246:249], v[18:33]
	v_lshl_add_u64 v[254:255], v[88:89], 0, s[12:13]
	s_mov_b32 m0, s93
	s_nop 0
	global_load_lds_dwordx4 v[254:255], off
	v_mfma_f32_32x32x16_bf16 v[50:65], v[250:253], v[242:245], v[50:65]
	v_mfma_f32_32x32x16_bf16 v[2:17], v[250:253], v[246:249], v[2:17]
	s_waitcnt lgkmcnt(0)
	ds_read_b128 v[238:241], v100 offset:16384
	ds_read_b128 v[242:245], v101
	ds_read_b128 v[246:249], v101 offset:4096
	ds_read_b128 v[250:253], v100 offset:20480
	v_mfma_f32_32x32x16_bf16 v[34:49], v[102:105], v[106:109], v[34:49]
	v_lshl_add_u64 v[254:255], v[90:91], 0, s[12:13]
	s_mov_b32 m0, s94
	s_nop 0
	global_load_lds_dwordx4 v[254:255], off
	v_mfma_f32_32x32x16_bf16 v[18:33], v[102:105], v[110:113], v[18:33]
	v_mfma_f32_32x32x16_bf16 v[50:65], v[114:117], v[106:109], v[50:65]
	v_mfma_f32_32x32x16_bf16 v[2:17], v[114:117], v[110:113], v[2:17]
	s_mov_b32 m0, s1
	s_waitcnt vmcnt(0) lgkmcnt(0)
	s_barrier
; template <class Epi>
; DI void gemm_phase(const u16* __restrict__ A, const u16* __restrict__ B, int mtiles, int ntiles, char* lds, const Epi& epi) {
;     ...
;         for (int kt = 0; kt < 16; ++kt) {
;             if (kt + 1 < 16) GSTAGE((kt + 1) & 1, kt + 1, ga, gb);
;             const char* sa = lds + (kt & 1) * 32768; const char* sb = sa + 16384;
; #pragma unroll
;             for (int ks = 0; ks < 4; ++ks) {
;                 bf16x8 fw[2], fx[2];
; #pragma unroll
;                 for (int ct = 0; ct < 2; ++ct) fw[ct] = *(const bf16x8*)(sb + swz(wn * 64 + ct * 32 + r, 2 * ks + h));
; #pragma unroll
;                 for (int tt = 0; tt < 2; ++tt) fx[tt] = *(const bf16x8*)(sa + swz(wm * 64 + tt * 32 + r, 2 * ks + h));
; #pragma unroll
;                 for (int ct = 0; ct < 2; ++ct)
; #pragma unroll
;                     for (int tt = 0; tt < 2; ++tt) acc[ct][tt] = __builtin_amdgcn_mfma_f32_32x32x16_bf16(fw[ct], fx[tt], acc[ct][tt], 0, 0, 0);
;             }
;             __syncthreads();
;         }
	ds_read_b128 v[102:105], v74 offset:49152
	ds_read_b128 v[106:109], v96 offset:32768
	ds_read_b128 v[110:113], v96 offset:36864
	ds_read_b128 v[114:117], v74 offset:53248
	v_mfma_f32_32x32x16_bf16 v[34:49], v[238:241], v[242:245], v[34:49]
	v_mfma_f32_32x32x16_bf16 v[18:33], v[238:241], v[246:249], v[18:33]
	v_lshl_add_u64 v[254:255], v[76:77], 0, s[14:15]
	global_load_lds_dwordx4 v[254:255], off
	v_lshl_add_u64 v[254:255], v[78:79], 0, s[14:15]
	s_mov_b32 m0, s7
	s_nop 0
	global_load_lds_dwordx4 v[254:255], off
	v_mfma_f32_32x32x16_bf16 v[50:65], v[250:253], v[242:245], v[50:65]
	v_lshl_add_u64 v[254:255], v[80:81], 0, s[14:15]
	s_mov_b32 m0, s38
	s_nop 0
	global_load_lds_dwordx4 v[254:255], off
	v_mfma_f32_32x32x16_bf16 v[2:17], v[250:253], v[246:249], v[2:17]
	s_waitcnt lgkmcnt(0)
	ds_read_b128 v[238:241], v95 offset:49152
	ds_read_b128 v[242:245], v97 offset:32768
	ds_read_b128 v[246:249], v97 offset:36864
	ds_read_b128 v[250:253], v95 offset:53248
	v_mfma_f32_32x32x16_bf16 v[34:49], v[102:105], v[106:109], v[34:49]
	v_lshl_add_u64 v[254:255], v[82:83], 0, s[14:15]
	s_mov_b32 m0, s39
	s_nop 0
	global_load_lds_dwordx4 v[254:255], off
	v_mfma_f32_32x32x16_bf16 v[18:33], v[102:105], v[110:113], v[18:33]
	v_lshl_add_u64 v[254:255], v[84:85], 0, s[14:15]
	s_mov_b32 m0, s50
	s_nop 0
	global_load_lds_dwordx4 v[254:255], off
	v_mfma_f32_32x32x16_bf16 v[50:65], v[114:117], v[106:109], v[50:65]
	v_mfma_f32_32x32x16_bf16 v[2:17], v[114:117], v[110:113], v[2:17]
	s_waitcnt lgkmcnt(0)
	ds_read_b128 v[102:105], v98 offset:49152
	ds_read_b128 v[106:109], v99 offset:32768
	ds_read_b128 v[110:113], v99 offset:36864
	ds_read_b128 v[114:117], v98 offset:53248
	v_mfma_f32_32x32x16_bf16 v[34:49], v[238:241], v[242:245], v[34:49]
	v_lshl_add_u64 v[254:255], v[86:87], 0, s[14:15]
	s_mov_b32 m0, s51
	s_nop 0
	global_load_lds_dwordx4 v[254:255], off
	v_mfma_f32_32x32x16_bf16 v[18:33], v[238:241], v[246:249], v[18:33]
	v_lshl_add_u64 v[254:255], v[88:89], 0, s[14:15]
	s_mov_b32 m0, s83
	s_nop 0
	global_load_lds_dwordx4 v[254:255], off
	v_mfma_f32_32x32x16_bf16 v[50:65], v[250:253], v[242:245], v[50:65]
	v_mfma_f32_32x32x16_bf16 v[2:17], v[250:253], v[246:249], v[2:17]
	s_waitcnt lgkmcnt(0)
	ds_read_b128 v[238:241], v100 offset:49152
	ds_read_b128 v[242:245], v101 offset:32768
	ds_read_b128 v[246:249], v101 offset:36864
	ds_read_b128 v[250:253], v100 offset:53248
	v_mfma_f32_32x32x16_bf16 v[34:49], v[102:105], v[106:109], v[34:49]
	v_lshl_add_u64 v[254:255], v[90:91], 0, s[14:15]
	s_mov_b32 m0, s90
	s_nop 0
	global_load_lds_dwordx4 v[254:255], off
	v_mfma_f32_32x32x16_bf16 v[18:33], v[102:105], v[110:113], v[18:33]
	v_mfma_f32_32x32x16_bf16 v[50:65], v[114:117], v[106:109], v[50:65]
	v_mfma_f32_32x32x16_bf16 v[2:17], v[114:117], v[110:113], v[2:17]
	s_mov_b32 m0, s86
	s_waitcnt vmcnt(0) lgkmcnt(0)
	s_barrier
	ds_read_b128 v[102:105], v74 offset:16384
	ds_read_b128 v[106:109], v96
	ds_read_b128 v[110:113], v96 offset:4096
	ds_read_b128 v[114:117], v74 offset:20480
	v_mfma_f32_32x32x16_bf16 v[34:49], v[238:241], v[242:245], v[34:49]
	v_mfma_f32_32x32x16_bf16 v[18:33], v[238:241], v[246:249], v[18:33]
	v_lshl_add_u64 v[254:255], v[76:77], 0, s[16:17]
	global_load_lds_dwordx4 v[254:255], off
	v_lshl_add_u64 v[254:255], v[78:79], 0, s[16:17]
	s_mov_b32 m0, s87
	s_nop 0
	global_load_lds_dwordx4 v[254:255], off
	v_mfma_f32_32x32x16_bf16 v[50:65], v[250:253], v[242:245], v[50:65]
	v_lshl_add_u64 v[254:255], v[80:81], 0, s[16:17]
	s_mov_b32 m0, s88
	s_nop 0
	global_load_lds_dwordx4 v[254:255], off
	v_mfma_f32_32x32x16_bf16 v[2:17], v[250:253], v[246:249], v[2:17]
	s_waitcnt lgkmcnt(0)
	ds_read_b128 v[238:241], v95 offset:16384
	ds_read_b128 v[242:245], v97
	ds_read_b128 v[246:249], v97 offset:4096
	ds_read_b128 v[250:253], v95 offset:20480
	v_mfma_f32_32x32x16_bf16 v[34:49], v[102:105], v[106:109], v[34:49]
	v_lshl_add_u64 v[254:255], v[82:83], 0, s[16:17]
	s_mov_b32 m0, s89
	s_nop 0
	global_load_lds_dwordx4 v[254:255], off
	v_mfma_f32_32x32x16_bf16 v[18:33], v[102:105], v[110:113], v[18:33]
	v_lshl_add_u64 v[254:255], v[84:85], 0, s[16:17]
	s_mov_b32 m0, s91
	s_nop 0
	global_load_lds_dwordx4 v[254:255], off
	v_mfma_f32_32x32x16_bf16 v[50:65], v[114:117], v[106:109], v[50:65]
	v_mfma_f32_32x32x16_bf16 v[2:17], v[114:117], v[110:113], v[2:17]
	s_waitcnt lgkmcnt(0)
	ds_read_b128 v[102:105], v98 offset:16384
	ds_read_b128 v[106:109], v99
	ds_read_b128 v[110:113], v99 offset:4096
	ds_read_b128 v[114:117], v98 offset:20480
	v_mfma_f32_32x32x16_bf16 v[34:49], v[238:241], v[242:245], v[34:49]
	v_lshl_add_u64 v[254:255], v[86:87], 0, s[16:17]
	s_mov_b32 m0, s92
	s_nop 0
	global_load_lds_dwordx4 v[254:255], off
	v_mfma_f32_32x32x16_bf16 v[18:33], v[238:241], v[246:249], v[18:33]
	v_lshl_add_u64 v[254:255], v[88:89], 0, s[16:17]
	s_mov_b32 m0, s93
	s_nop 0
	global_load_lds_dwordx4 v[254:255], off
	v_mfma_f32_32x32x16_bf16 v[50:65], v[250:253], v[242:245], v[50:65]
	v_mfma_f32_32x32x16_bf16 v[2:17], v[250:253], v[246:249], v[2:17]
	s_waitcnt lgkmcnt(0)
	ds_read_b128 v[238:241], v100 offset:16384
	ds_read_b128 v[242:245], v101
	ds_read_b128 v[246:249], v101 offset:4096
	ds_read_b128 v[250:253], v100 offset:20480
	v_mfma_f32_32x32x16_bf16 v[34:49], v[102:105], v[106:109], v[34:49]
	v_lshl_add_u64 v[254:255], v[90:91], 0, s[16:17]
	s_mov_b32 m0, s94
	s_nop 0
	global_load_lds_dwordx4 v[254:255], off
	v_mfma_f32_32x32x16_bf16 v[18:33], v[102:105], v[110:113], v[18:33]
	v_mfma_f32_32x32x16_bf16 v[50:65], v[114:117], v[106:109], v[50:65]
	v_mfma_f32_32x32x16_bf16 v[2:17], v[114:117], v[110:113], v[2:17]
	s_mov_b32 m0, s1
	s_waitcnt vmcnt(0) lgkmcnt(0)
	s_barrier
; template <class Epi>
; DI void gemm_phase(const u16* __restrict__ A, const u16* __restrict__ B, int mtiles, int ntiles, char* lds, const Epi& epi) {
;     ...
;         for (int kt = 0; kt < 16; ++kt) {
;             if (kt + 1 < 16) GSTAGE((kt + 1) & 1, kt + 1, ga, gb);
;             const char* sa = lds + (kt & 1) * 32768; const char* sb = sa + 16384;
; #pragma unroll
;             for (int ks = 0; ks < 4; ++ks) {
;                 bf16x8 fw[2], fx[2];
; #pragma unroll
;                 for (int ct = 0; ct < 2; ++ct) fw[ct] = *(const bf16x8*)(sb + swz(wn * 64 + ct * 32 + r, 2 * ks + h));
; #pragma unroll
;                 for (int tt = 0; tt < 2; ++tt) fx[tt] = *(const bf16x8*)(sa + swz(wm * 64 + tt * 32 + r, 2 * ks + h));
; #pragma unroll
;                 for (int ct = 0; ct < 2; ++ct)
; #pragma unroll
;                     for (int tt = 0; tt < 2; ++tt) acc[ct][tt] = __builtin_amdgcn_mfma_f32_32x32x16_bf16(fw[ct], fx[tt], acc[ct][tt], 0, 0, 0);
;             }
;             __syncthreads();
;         }
	ds_read_b128 v[102:105], v74 offset:49152
	ds_read_b128 v[106:109], v96 offset:32768
	ds_read_b128 v[110:113], v96 offset:36864
	ds_read_b128 v[114:117], v74 offset:53248
	v_mfma_f32_32x32x16_bf16 v[34:49], v[238:241], v[242:245], v[34:49]
	v_mfma_f32_32x32x16_bf16 v[18:33], v[238:241], v[246:249], v[18:33]
	v_lshl_add_u64 v[254:255], v[76:77], 0, s[18:19]
	global_load_lds_dwordx4 v[254:255], off
	v_lshl_add_u64 v[254:255], v[78:79], 0, s[18:19]
	s_mov_b32 m0, s7
	s_nop 0
	global_load_lds_dwordx4 v[254:255], off
	v_mfma_f32_32x32x16_bf16 v[50:65], v[250:253], v[242:245], v[50:65]
	v_lshl_add_u64 v[254:255], v[80:81], 0, s[18:19]
	s_mov_b32 m0, s38
	s_nop 0
	global_load_lds_dwordx4 v[254:255], off
	v_mfma_f32_32x32x16_bf16 v[2:17], v[250:253], v[246:249], v[2:17]
	s_waitcnt lgkmcnt(0)
	ds_read_b128 v[238:241], v95 offset:49152
	ds_read_b128 v[242:245], v97 offset:32768
	ds_read_b128 v[246:249], v97 offset:36864
	ds_read_b128 v[250:253], v95 offset:53248
	v_mfma_f32_32x32x16_bf16 v[34:49], v[102:105], v[106:109], v[34:49]
	v_lshl_add_u64 v[254:255], v[82:83], 0, s[18:19]
	s_mov_b32 m0, s39
	s_nop 0
	global_load_lds_dwordx4 v[254:255], off
	v_mfma_f32_32x32x16_bf16 v[18:33], v[102:105], v[110:113], v[18:33]
	v_lshl_add_u64 v[254:255], v[84:85], 0, s[18:19]
	s_mov_b32 m0, s50
	s_nop 0
	global_load_lds_dwordx4 v[254:255], off
	v_mfma_f32_32x32x16_bf16 v[50:65], v[114:117], v[106:109], v[50:65]
	v_mfma_f32_32x32x16_bf16 v[2:17], v[114:117], v[110:113], v[2:17]
	s_waitcnt lgkmcnt(0)
	ds_read_b128 v[102:105], v98 offset:49152
	ds_read_b128 v[106:109], v99 offset:32768
	ds_read_b128 v[110:113], v99 offset:36864
	ds_read_b128 v[114:117], v98 offset:53248
	v_mfma_f32_32x32x16_bf16 v[34:49], v[238:241], v[242:245], v[34:49]
	v_lshl_add_u64 v[254:255], v[86:87], 0, s[18:19]
	s_mov_b32 m0, s51
	s_nop 0
	global_load_lds_dwordx4 v[254:255], off
	v_mfma_f32_32x32x16_bf16 v[18:33], v[238:241], v[246:249], v[18:33]
	v_lshl_add_u64 v[254:255], v[88:89], 0, s[18:19]
	s_mov_b32 m0, s83
	s_nop 0
	global_load_lds_dwordx4 v[254:255], off
	v_mfma_f32_32x32x16_bf16 v[50:65], v[250:253], v[242:245], v[50:65]
	v_mfma_f32_32x32x16_bf16 v[2:17], v[250:253], v[246:249], v[2:17]
	s_waitcnt lgkmcnt(0)
	ds_read_b128 v[238:241], v100 offset:49152
	ds_read_b128 v[242:245], v101 offset:32768
	ds_read_b128 v[246:249], v101 offset:36864
	ds_read_b128 v[250:253], v100 offset:53248
	v_mfma_f32_32x32x16_bf16 v[34:49], v[102:105], v[106:109], v[34:49]
	v_lshl_add_u64 v[254:255], v[90:91], 0, s[18:19]
	s_mov_b32 m0, s90
	s_nop 0
	global_load_lds_dwordx4 v[254:255], off
	v_mfma_f32_32x32x16_bf16 v[18:33], v[102:105], v[110:113], v[18:33]
	v_mfma_f32_32x32x16_bf16 v[50:65], v[114:117], v[106:109], v[50:65]
	v_mfma_f32_32x32x16_bf16 v[2:17], v[114:117], v[110:113], v[2:17]
	s_mov_b32 m0, s86
	s_waitcnt vmcnt(0) lgkmcnt(0)
	s_barrier
	ds_read_b128 v[102:105], v74 offset:16384
	ds_read_b128 v[106:109], v96
	ds_read_b128 v[110:113], v96 offset:4096
	ds_read_b128 v[114:117], v74 offset:20480
	v_mfma_f32_32x32x16_bf16 v[34:49], v[238:241], v[242:245], v[34:49]
	v_mfma_f32_32x32x16_bf16 v[18:33], v[238:241], v[246:249], v[18:33]
	v_lshl_add_u64 v[254:255], v[76:77], 0, s[20:21]
	global_load_lds_dwordx4 v[254:255], off
	v_lshl_add_u64 v[254:255], v[78:79], 0, s[20:21]
	s_mov_b32 m0, s87
	s_nop 0
	global_load_lds_dwordx4 v[254:255], off
	v_mfma_f32_32x32x16_bf16 v[50:65], v[250:253], v[242:245], v[50:65]
	v_lshl_add_u64 v[254:255], v[80:81], 0, s[20:21]
	s_mov_b32 m0, s88
	s_nop 0
	global_load_lds_dwordx4 v[254:255], off
	v_mfma_f32_32x32x16_bf16 v[2:17], v[250:253], v[246:249], v[2:17]
	s_waitcnt lgkmcnt(0)
	ds_read_b128 v[238:241], v95 offset:16384
	ds_read_b128 v[242:245], v97
	ds_read_b128 v[246:249], v97 offset:4096
	ds_read_b128 v[250:253], v95 offset:20480
	v_mfma_f32_32x32x16_bf16 v[34:49], v[102:105], v[106:109], v[34:49]
	v_lshl_add_u64 v[254:255], v[82:83], 0, s[20:21]
	s_mov_b32 m0, s89
	s_nop 0
	global_load_lds_dwordx4 v[254:255], off
	v_mfma_f32_32x32x16_bf16 v[18:33], v[102:105], v[110:113], v[18:33]
	v_lshl_add_u64 v[254:255], v[84:85], 0, s[20:21]
	s_mov_b32 m0, s91
	s_nop 0
	global_load_lds_dwordx4 v[254:255], off
	v_mfma_f32_32x32x16_bf16 v[50:65], v[114:117], v[106:109], v[50:65]
	v_mfma_f32_32x32x16_bf16 v[2:17], v[114:117], v[110:113], v[2:17]
	s_waitcnt lgkmcnt(0)
	ds_read_b128 v[102:105], v98 offset:16384
	ds_read_b128 v[106:109], v99
	ds_read_b128 v[110:113], v99 offset:4096
	ds_read_b128 v[114:117], v98 offset:20480
	v_mfma_f32_32x32x16_bf16 v[34:49], v[238:241], v[242:245], v[34:49]
	v_lshl_add_u64 v[254:255], v[86:87], 0, s[20:21]
	s_mov_b32 m0, s92
	s_nop 0
	global_load_lds_dwordx4 v[254:255], off
	v_mfma_f32_32x32x16_bf16 v[18:33], v[238:241], v[246:249], v[18:33]
	v_lshl_add_u64 v[254:255], v[88:89], 0, s[20:21]
	s_mov_b32 m0, s93
	s_nop 0
	global_load_lds_dwordx4 v[254:255], off
	v_mfma_f32_32x32x16_bf16 v[50:65], v[250:253], v[242:245], v[50:65]
	v_mfma_f32_32x32x16_bf16 v[2:17], v[250:253], v[246:249], v[2:17]
	s_waitcnt lgkmcnt(0)
	ds_read_b128 v[238:241], v100 offset:16384
	ds_read_b128 v[242:245], v101
	ds_read_b128 v[246:249], v101 offset:4096
	ds_read_b128 v[250:253], v100 offset:20480
	v_mfma_f32_32x32x16_bf16 v[34:49], v[102:105], v[106:109], v[34:49]
	v_lshl_add_u64 v[254:255], v[90:91], 0, s[20:21]
	s_mov_b32 m0, s94
	s_nop 0
	global_load_lds_dwordx4 v[254:255], off
	v_mfma_f32_32x32x16_bf16 v[18:33], v[102:105], v[110:113], v[18:33]
	v_mfma_f32_32x32x16_bf16 v[50:65], v[114:117], v[106:109], v[50:65]
	v_mfma_f32_32x32x16_bf16 v[2:17], v[114:117], v[110:113], v[2:17]
	s_mov_b32 m0, s1
	s_waitcnt vmcnt(0) lgkmcnt(0)
	s_barrier
; template <class Epi>
; DI void gemm_phase(const u16* __restrict__ A, const u16* __restrict__ B, int mtiles, int ntiles, char* lds, const Epi& epi) {
;     ...
;         for (int kt = 0; kt < 16; ++kt) {
;             if (kt + 1 < 16) GSTAGE((kt + 1) & 1, kt + 1, ga, gb);
;             const char* sa = lds + (kt & 1) * 32768; const char* sb = sa + 16384;
; #pragma unroll
;             for (int ks = 0; ks < 4; ++ks) {
;                 bf16x8 fw[2], fx[2];
; #pragma unroll
;                 for (int ct = 0; ct < 2; ++ct) fw[ct] = *(const bf16x8*)(sb + swz(wn * 64 + ct * 32 + r, 2 * ks + h));
; #pragma unroll
;                 for (int tt = 0; tt < 2; ++tt) fx[tt] = *(const bf16x8*)(sa + swz(wm * 64 + tt * 32 + r, 2 * ks + h));
; #pragma unroll
;                 for (int ct = 0; ct < 2; ++ct)
; #pragma unroll
;                     for (int tt = 0; tt < 2; ++tt) acc[ct][tt] = __builtin_amdgcn_mfma_f32_32x32x16_bf16(fw[ct], fx[tt], acc[ct][tt], 0, 0, 0);
;             }
;             __syncthreads();
;         }
	ds_read_b128 v[102:105], v74 offset:49152
	ds_read_b128 v[106:109], v96 offset:32768
	ds_read_b128 v[110:113], v96 offset:36864
	ds_read_b128 v[114:117], v74 offset:53248
	v_mfma_f32_32x32x16_bf16 v[34:49], v[238:241], v[242:245], v[34:49]
	v_mfma_f32_32x32x16_bf16 v[18:33], v[238:241], v[246:249], v[18:33]
	v_lshl_add_u64 v[254:255], v[76:77], 0, s[22:23]
	global_load_lds_dwordx4 v[254:255], off
	v_lshl_add_u64 v[254:255], v[78:79], 0, s[22:23]
	s_mov_b32 m0, s7
	s_nop 0
	global_load_lds_dwordx4 v[254:255], off
	v_mfma_f32_32x32x16_bf16 v[50:65], v[250:253], v[242:245], v[50:65]
	v_lshl_add_u64 v[254:255], v[80:81], 0, s[22:23]
	s_mov_b32 m0, s38
	s_nop 0
	global_load_lds_dwordx4 v[254:255], off
	v_mfma_f32_32x32x16_bf16 v[2:17], v[250:253], v[246:249], v[2:17]
	s_waitcnt lgkmcnt(0)
	ds_read_b128 v[238:241], v95 offset:49152
	ds_read_b128 v[242:245], v97 offset:32768
	ds_read_b128 v[246:249], v97 offset:36864
	ds_read_b128 v[250:253], v95 offset:53248
	v_mfma_f32_32x32x16_bf16 v[34:49], v[102:105], v[106:109], v[34:49]
	v_lshl_add_u64 v[254:255], v[82:83], 0, s[22:23]
	s_mov_b32 m0, s39
	s_nop 0
	global_load_lds_dwordx4 v[254:255], off
	v_mfma_f32_32x32x16_bf16 v[18:33], v[102:105], v[110:113], v[18:33]
	v_lshl_add_u64 v[254:255], v[84:85], 0, s[22:23]
	s_mov_b32 m0, s50
	s_nop 0
	global_load_lds_dwordx4 v[254:255], off
	v_mfma_f32_32x32x16_bf16 v[50:65], v[114:117], v[106:109], v[50:65]
	v_mfma_f32_32x32x16_bf16 v[2:17], v[114:117], v[110:113], v[2:17]
	s_waitcnt lgkmcnt(0)
	ds_read_b128 v[102:105], v98 offset:49152
	ds_read_b128 v[106:109], v99 offset:32768
	ds_read_b128 v[110:113], v99 offset:36864
	ds_read_b128 v[114:117], v98 offset:53248
	v_mfma_f32_32x32x16_bf16 v[34:49], v[238:241], v[242:245], v[34:49]
	v_lshl_add_u64 v[254:255], v[86:87], 0, s[22:23]
	s_mov_b32 m0, s51
	s_nop 0
	global_load_lds_dwordx4 v[254:255], off
	v_mfma_f32_32x32x16_bf16 v[18:33], v[238:241], v[246:249], v[18:33]
	v_lshl_add_u64 v[254:255], v[88:89], 0, s[22:23]
	s_mov_b32 m0, s83
	s_nop 0
	global_load_lds_dwordx4 v[254:255], off
	v_mfma_f32_32x32x16_bf16 v[50:65], v[250:253], v[242:245], v[50:65]
	v_mfma_f32_32x32x16_bf16 v[2:17], v[250:253], v[246:249], v[2:17]
	s_waitcnt lgkmcnt(0)
	ds_read_b128 v[238:241], v100 offset:49152
	ds_read_b128 v[242:245], v101 offset:32768
	ds_read_b128 v[246:249], v101 offset:36864
	ds_read_b128 v[250:253], v100 offset:53248
	v_mfma_f32_32x32x16_bf16 v[34:49], v[102:105], v[106:109], v[34:49]
	v_lshl_add_u64 v[254:255], v[90:91], 0, s[22:23]
	s_mov_b32 m0, s90
	s_nop 0
	global_load_lds_dwordx4 v[254:255], off
	v_mfma_f32_32x32x16_bf16 v[18:33], v[102:105], v[110:113], v[18:33]
	v_mfma_f32_32x32x16_bf16 v[50:65], v[114:117], v[106:109], v[50:65]
	v_mfma_f32_32x32x16_bf16 v[2:17], v[114:117], v[110:113], v[2:17]
	s_mov_b32 m0, s86
	s_waitcnt vmcnt(0) lgkmcnt(0)
	s_barrier
	ds_read_b128 v[102:105], v74 offset:16384
	ds_read_b128 v[106:109], v96
	ds_read_b128 v[110:113], v96 offset:4096
	ds_read_b128 v[114:117], v74 offset:20480
	v_mfma_f32_32x32x16_bf16 v[34:49], v[238:241], v[242:245], v[34:49]
	v_mfma_f32_32x32x16_bf16 v[18:33], v[238:241], v[246:249], v[18:33]
	v_lshl_add_u64 v[254:255], v[76:77], 0, s[24:25]
	global_load_lds_dwordx4 v[254:255], off
	v_lshl_add_u64 v[254:255], v[78:79], 0, s[24:25]
	s_mov_b32 m0, s87
	s_nop 0
	global_load_lds_dwordx4 v[254:255], off
	v_mfma_f32_32x32x16_bf16 v[50:65], v[250:253], v[242:245], v[50:65]
	v_lshl_add_u64 v[254:255], v[80:81], 0, s[24:25]
	s_mov_b32 m0, s88
	s_nop 0
	global_load_lds_dwordx4 v[254:255], off
	v_mfma_f32_32x32x16_bf16 v[2:17], v[250:253], v[246:249], v[2:17]
	s_waitcnt lgkmcnt(0)
	ds_read_b128 v[238:241], v95 offset:16384
	ds_read_b128 v[242:245], v97
	ds_read_b128 v[246:249], v97 offset:4096
	ds_read_b128 v[250:253], v95 offset:20480
	v_mfma_f32_32x32x16_bf16 v[34:49], v[102:105], v[106:109], v[34:49]
	v_lshl_add_u64 v[254:255], v[82:83], 0, s[24:25]
	s_mov_b32 m0, s89
	s_nop 0
	global_load_lds_dwordx4 v[254:255], off
	v_mfma_f32_32x32x16_bf16 v[18:33], v[102:105], v[110:113], v[18:33]
	v_lshl_add_u64 v[254:255], v[84:85], 0, s[24:25]
	s_mov_b32 m0, s91
	s_nop 0
	global_load_lds_dwordx4 v[254:255], off
	v_mfma_f32_32x32x16_bf16 v[50:65], v[114:117], v[106:109], v[50:65]
	v_mfma_f32_32x32x16_bf16 v[2:17], v[114:117], v[110:113], v[2:17]
	s_waitcnt lgkmcnt(0)
	ds_read_b128 v[102:105], v98 offset:16384
	ds_read_b128 v[106:109], v99
	ds_read_b128 v[110:113], v99 offset:4096
	ds_read_b128 v[114:117], v98 offset:20480
	v_mfma_f32_32x32x16_bf16 v[34:49], v[238:241], v[242:245], v[34:49]
	v_lshl_add_u64 v[254:255], v[86:87], 0, s[24:25]
	s_mov_b32 m0, s92
	s_nop 0
	global_load_lds_dwordx4 v[254:255], off
	v_mfma_f32_32x32x16_bf16 v[18:33], v[238:241], v[246:249], v[18:33]
	v_lshl_add_u64 v[254:255], v[88:89], 0, s[24:25]
	s_mov_b32 m0, s93
	s_nop 0
	global_load_lds_dwordx4 v[254:255], off
	v_mfma_f32_32x32x16_bf16 v[50:65], v[250:253], v[242:245], v[50:65]
	v_mfma_f32_32x32x16_bf16 v[2:17], v[250:253], v[246:249], v[2:17]
	s_waitcnt lgkmcnt(0)
	ds_read_b128 v[238:241], v100 offset:16384
	ds_read_b128 v[242:245], v101
	ds_read_b128 v[246:249], v101 offset:4096
	ds_read_b128 v[250:253], v100 offset:20480
	v_mfma_f32_32x32x16_bf16 v[34:49], v[102:105], v[106:109], v[34:49]
	v_lshl_add_u64 v[254:255], v[90:91], 0, s[24:25]
	s_mov_b32 m0, s94
	s_nop 0
	global_load_lds_dwordx4 v[254:255], off
	v_mfma_f32_32x32x16_bf16 v[18:33], v[102:105], v[110:113], v[18:33]
	v_mfma_f32_32x32x16_bf16 v[50:65], v[114:117], v[106:109], v[50:65]
	v_mfma_f32_32x32x16_bf16 v[2:17], v[114:117], v[110:113], v[2:17]
	s_mov_b32 m0, s1
	s_waitcnt vmcnt(0) lgkmcnt(0)
	s_barrier
; template <class Epi>
; DI void gemm_phase(const u16* __restrict__ A, const u16* __restrict__ B, int mtiles, int ntiles, char* lds, const Epi& epi) {
;     ...
;         for (int kt = 0; kt < 16; ++kt) {
;             if (kt + 1 < 16) GSTAGE((kt + 1) & 1, kt + 1, ga, gb);
;             const char* sa = lds + (kt & 1) * 32768; const char* sb = sa + 16384;
; #pragma unroll
;             for (int ks = 0; ks < 4; ++ks) {
;                 bf16x8 fw[2], fx[2];
; #pragma unroll
;                 for (int ct = 0; ct < 2; ++ct) fw[ct] = *(const bf16x8*)(sb + swz(wn * 64 + ct * 32 + r, 2 * ks + h));
; #pragma unroll
;                 for (int tt = 0; tt < 2; ++tt) fx[tt] = *(const bf16x8*)(sa + swz(wm * 64 + tt * 32 + r, 2 * ks + h));
; #pragma unroll
;                 for (int ct = 0; ct < 2; ++ct)
; #pragma unroll
;                     for (int tt = 0; tt < 2; ++tt) acc[ct][tt] = __builtin_amdgcn_mfma_f32_32x32x16_bf16(fw[ct], fx[tt], acc[ct][tt], 0, 0, 0);
;             }
;             __syncthreads();
;         }
	ds_read_b128 v[102:105], v74 offset:49152
	ds_read_b128 v[106:109], v96 offset:32768
	ds_read_b128 v[110:113], v96 offset:36864
	ds_read_b128 v[114:117], v74 offset:53248
	v_mfma_f32_32x32x16_bf16 v[34:49], v[238:241], v[242:245], v[34:49]
	v_mfma_f32_32x32x16_bf16 v[18:33], v[238:241], v[246:249], v[18:33]
	v_lshl_add_u64 v[254:255], v[76:77], 0, s[26:27]
	global_load_lds_dwordx4 v[254:255], off
	v_lshl_add_u64 v[254:255], v[78:79], 0, s[26:27]
	s_mov_b32 m0, s7
	s_nop 0
	global_load_lds_dwordx4 v[254:255], off
	v_mfma_f32_32x32x16_bf16 v[50:65], v[250:253], v[242:245], v[50:65]
	v_lshl_add_u64 v[254:255], v[80:81], 0, s[26:27]
	s_mov_b32 m0, s38
	s_nop 0
	global_load_lds_dwordx4 v[254:255], off
	v_mfma_f32_32x32x16_bf16 v[2:17], v[250:253], v[246:249], v[2:17]
	s_waitcnt lgkmcnt(0)
	ds_read_b128 v[238:241], v95 offset:49152
	ds_read_b128 v[242:245], v97 offset:32768
	ds_read_b128 v[246:249], v97 offset:36864
	ds_read_b128 v[250:253], v95 offset:53248
	v_mfma_f32_32x32x16_bf16 v[34:49], v[102:105], v[106:109], v[34:49]
	v_lshl_add_u64 v[254:255], v[82:83], 0, s[26:27]
	s_mov_b32 m0, s39
	s_nop 0
	global_load_lds_dwordx4 v[254:255], off
	v_mfma_f32_32x32x16_bf16 v[18:33], v[102:105], v[110:113], v[18:33]
	v_lshl_add_u64 v[254:255], v[84:85], 0, s[26:27]
	s_mov_b32 m0, s50
	s_nop 0
	global_load_lds_dwordx4 v[254:255], off
	v_mfma_f32_32x32x16_bf16 v[50:65], v[114:117], v[106:109], v[50:65]
	v_mfma_f32_32x32x16_bf16 v[2:17], v[114:117], v[110:113], v[2:17]
	s_waitcnt lgkmcnt(0)
	ds_read_b128 v[102:105], v98 offset:49152
	ds_read_b128 v[106:109], v99 offset:32768
	ds_read_b128 v[110:113], v99 offset:36864
	ds_read_b128 v[114:117], v98 offset:53248
	v_mfma_f32_32x32x16_bf16 v[34:49], v[238:241], v[242:245], v[34:49]
	v_lshl_add_u64 v[254:255], v[86:87], 0, s[26:27]
	s_mov_b32 m0, s51
	s_nop 0
	global_load_lds_dwordx4 v[254:255], off
	v_mfma_f32_32x32x16_bf16 v[18:33], v[238:241], v[246:249], v[18:33]
	v_lshl_add_u64 v[254:255], v[88:89], 0, s[26:27]
	s_mov_b32 m0, s83
	s_nop 0
	global_load_lds_dwordx4 v[254:255], off
	v_mfma_f32_32x32x16_bf16 v[50:65], v[250:253], v[242:245], v[50:65]
	v_mfma_f32_32x32x16_bf16 v[2:17], v[250:253], v[246:249], v[2:17]
	s_waitcnt lgkmcnt(0)
	ds_read_b128 v[238:241], v100 offset:49152
	ds_read_b128 v[242:245], v101 offset:32768
	ds_read_b128 v[246:249], v101 offset:36864
	ds_read_b128 v[250:253], v100 offset:53248
	v_mfma_f32_32x32x16_bf16 v[34:49], v[102:105], v[106:109], v[34:49]
	v_lshl_add_u64 v[254:255], v[90:91], 0, s[26:27]
	s_mov_b32 m0, s90
	s_nop 0
	global_load_lds_dwordx4 v[254:255], off
	v_mfma_f32_32x32x16_bf16 v[18:33], v[102:105], v[110:113], v[18:33]
	v_mfma_f32_32x32x16_bf16 v[50:65], v[114:117], v[106:109], v[50:65]
	v_mfma_f32_32x32x16_bf16 v[2:17], v[114:117], v[110:113], v[2:17]
	s_mov_b32 m0, s86
	s_waitcnt vmcnt(0) lgkmcnt(0)
	s_barrier
	ds_read_b128 v[102:105], v74 offset:16384
	ds_read_b128 v[106:109], v96
	ds_read_b128 v[110:113], v96 offset:4096
	ds_read_b128 v[114:117], v74 offset:20480
	v_mfma_f32_32x32x16_bf16 v[34:49], v[238:241], v[242:245], v[34:49]
	v_mfma_f32_32x32x16_bf16 v[18:33], v[238:241], v[246:249], v[18:33]
	v_lshl_add_u64 v[254:255], v[76:77], 0, s[28:29]
	global_load_lds_dwordx4 v[254:255], off
	v_lshl_add_u64 v[254:255], v[78:79], 0, s[28:29]
	s_mov_b32 m0, s87
	s_nop 0
	global_load_lds_dwordx4 v[254:255], off
	v_mfma_f32_32x32x16_bf16 v[50:65], v[250:253], v[242:245], v[50:65]
	v_lshl_add_u64 v[254:255], v[80:81], 0, s[28:29]
	s_mov_b32 m0, s88
	s_nop 0
	global_load_lds_dwordx4 v[254:255], off
	v_mfma_f32_32x32x16_bf16 v[2:17], v[250:253], v[246:249], v[2:17]
	s_waitcnt lgkmcnt(0)
	ds_read_b128 v[238:241], v95 offset:16384
	ds_read_b128 v[242:245], v97
	ds_read_b128 v[246:249], v97 offset:4096
	ds_read_b128 v[250:253], v95 offset:20480
	v_mfma_f32_32x32x16_bf16 v[34:49], v[102:105], v[106:109], v[34:49]
	v_lshl_add_u64 v[254:255], v[82:83], 0, s[28:29]
	s_mov_b32 m0, s89
	s_nop 0
	global_load_lds_dwordx4 v[254:255], off
	v_mfma_f32_32x32x16_bf16 v[18:33], v[102:105], v[110:113], v[18:33]
	v_lshl_add_u64 v[254:255], v[84:85], 0, s[28:29]
	s_mov_b32 m0, s91
	s_nop 0
	global_load_lds_dwordx4 v[254:255], off
	v_mfma_f32_32x32x16_bf16 v[50:65], v[114:117], v[106:109], v[50:65]
	v_mfma_f32_32x32x16_bf16 v[2:17], v[114:117], v[110:113], v[2:17]
	s_waitcnt lgkmcnt(0)
	ds_read_b128 v[102:105], v98 offset:16384
	ds_read_b128 v[106:109], v99
	ds_read_b128 v[110:113], v99 offset:4096
	ds_read_b128 v[114:117], v98 offset:20480
	v_mfma_f32_32x32x16_bf16 v[34:49], v[238:241], v[242:245], v[34:49]
	v_lshl_add_u64 v[254:255], v[86:87], 0, s[28:29]
	s_mov_b32 m0, s92
	s_nop 0
	global_load_lds_dwordx4 v[254:255], off
	v_mfma_f32_32x32x16_bf16 v[18:33], v[238:241], v[246:249], v[18:33]
	v_lshl_add_u64 v[254:255], v[88:89], 0, s[28:29]
	s_mov_b32 m0, s93
	s_nop 0
	global_load_lds_dwordx4 v[254:255], off
	v_mfma_f32_32x32x16_bf16 v[50:65], v[250:253], v[242:245], v[50:65]
	v_mfma_f32_32x32x16_bf16 v[2:17], v[250:253], v[246:249], v[2:17]
	s_waitcnt lgkmcnt(0)
	ds_read_b128 v[238:241], v100 offset:16384
	ds_read_b128 v[242:245], v101
	ds_read_b128 v[246:249], v101 offset:4096
	ds_read_b128 v[250:253], v100 offset:20480
	v_mfma_f32_32x32x16_bf16 v[34:49], v[102:105], v[106:109], v[34:49]
	v_lshl_add_u64 v[254:255], v[90:91], 0, s[28:29]
	s_mov_b32 m0, s94
	s_nop 0
	global_load_lds_dwordx4 v[254:255], off
	v_mfma_f32_32x32x16_bf16 v[18:33], v[102:105], v[110:113], v[18:33]
	v_mfma_f32_32x32x16_bf16 v[50:65], v[114:117], v[106:109], v[50:65]
	v_mfma_f32_32x32x16_bf16 v[2:17], v[114:117], v[110:113], v[2:17]
	s_mov_b32 m0, s1
	s_waitcnt vmcnt(0) lgkmcnt(0)
	s_barrier
; template <class Epi>
; DI void gemm_phase(const u16* __restrict__ A, const u16* __restrict__ B, int mtiles, int ntiles, char* lds, const Epi& epi) {
;     ...
;         for (int kt = 0; kt < 16; ++kt) {
;             if (kt + 1 < 16) GSTAGE((kt + 1) & 1, kt + 1, ga, gb);
;             const char* sa = lds + (kt & 1) * 32768; const char* sb = sa + 16384;
; #pragma unroll
;             for (int ks = 0; ks < 4; ++ks) {
;                 bf16x8 fw[2], fx[2];
; #pragma unroll
;                 for (int ct = 0; ct < 2; ++ct) fw[ct] = *(const bf16x8*)(sb + swz(wn * 64 + ct * 32 + r, 2 * ks + h));
; #pragma unroll
;                 for (int tt = 0; tt < 2; ++tt) fx[tt] = *(const bf16x8*)(sa + swz(wm * 64 + tt * 32 + r, 2 * ks + h));
; #pragma unroll
;                 for (int ct = 0; ct < 2; ++ct)
; #pragma unroll
;                     for (int tt = 0; tt < 2; ++tt) acc[ct][tt] = __builtin_amdgcn_mfma_f32_32x32x16_bf16(fw[ct], fx[tt], acc[ct][tt], 0, 0, 0);
;             }
;             __syncthreads();
;         }
	ds_read_b128 v[102:105], v74 offset:49152
	ds_read_b128 v[106:109], v96 offset:32768
	ds_read_b128 v[110:113], v96 offset:36864
	ds_read_b128 v[114:117], v74 offset:53248
	v_mfma_f32_32x32x16_bf16 v[34:49], v[238:241], v[242:245], v[34:49]
	v_mfma_f32_32x32x16_bf16 v[18:33], v[238:241], v[246:249], v[18:33]
	v_lshl_add_u64 v[254:255], v[76:77], 0, s[30:31]
	global_load_lds_dwordx4 v[254:255], off
	v_lshl_add_u64 v[254:255], v[78:79], 0, s[30:31]
	s_mov_b32 m0, s7
	s_nop 0
	global_load_lds_dwordx4 v[254:255], off
	v_mfma_f32_32x32x16_bf16 v[50:65], v[250:253], v[242:245], v[50:65]
	v_lshl_add_u64 v[254:255], v[80:81], 0, s[30:31]
	s_mov_b32 m0, s38
	s_nop 0
	global_load_lds_dwordx4 v[254:255], off
	v_mfma_f32_32x32x16_bf16 v[2:17], v[250:253], v[246:249], v[2:17]
	s_waitcnt lgkmcnt(0)
	ds_read_b128 v[238:241], v95 offset:49152
	ds_read_b128 v[242:245], v97 offset:32768
	ds_read_b128 v[246:249], v97 offset:36864
	ds_read_b128 v[250:253], v95 offset:53248
	v_mfma_f32_32x32x16_bf16 v[34:49], v[102:105], v[106:109], v[34:49]
	v_lshl_add_u64 v[254:255], v[82:83], 0, s[30:31]
	s_mov_b32 m0, s39
	s_nop 0
	global_load_lds_dwordx4 v[254:255], off
	v_mfma_f32_32x32x16_bf16 v[18:33], v[102:105], v[110:113], v[18:33]
	v_lshl_add_u64 v[254:255], v[84:85], 0, s[30:31]
	s_mov_b32 m0, s50
	s_nop 0
	global_load_lds_dwordx4 v[254:255], off
	v_mfma_f32_32x32x16_bf16 v[50:65], v[114:117], v[106:109], v[50:65]
	v_mfma_f32_32x32x16_bf16 v[2:17], v[114:117], v[110:113], v[2:17]
	s_waitcnt lgkmcnt(0)
	ds_read_b128 v[102:105], v98 offset:49152
	ds_read_b128 v[106:109], v99 offset:32768
	ds_read_b128 v[110:113], v99 offset:36864
	ds_read_b128 v[114:117], v98 offset:53248
	v_mfma_f32_32x32x16_bf16 v[34:49], v[238:241], v[242:245], v[34:49]
	v_lshl_add_u64 v[254:255], v[86:87], 0, s[30:31]
	s_mov_b32 m0, s51
	s_nop 0
	global_load_lds_dwordx4 v[254:255], off
	v_mfma_f32_32x32x16_bf16 v[18:33], v[238:241], v[246:249], v[18:33]
	v_lshl_add_u64 v[254:255], v[88:89], 0, s[30:31]
	s_mov_b32 m0, s83
	s_nop 0
	global_load_lds_dwordx4 v[254:255], off
	v_mfma_f32_32x32x16_bf16 v[50:65], v[250:253], v[242:245], v[50:65]
	v_mfma_f32_32x32x16_bf16 v[2:17], v[250:253], v[246:249], v[2:17]
	s_waitcnt lgkmcnt(0)
	ds_read_b128 v[238:241], v100 offset:49152
	ds_read_b128 v[242:245], v101 offset:32768
	ds_read_b128 v[246:249], v101 offset:36864
	ds_read_b128 v[250:253], v100 offset:53248
	v_mfma_f32_32x32x16_bf16 v[34:49], v[102:105], v[106:109], v[34:49]
	v_lshl_add_u64 v[254:255], v[90:91], 0, s[30:31]
	s_mov_b32 m0, s90
	s_nop 0
	global_load_lds_dwordx4 v[254:255], off
	v_mfma_f32_32x32x16_bf16 v[18:33], v[102:105], v[110:113], v[18:33]
	v_mfma_f32_32x32x16_bf16 v[50:65], v[114:117], v[106:109], v[50:65]
	v_mfma_f32_32x32x16_bf16 v[2:17], v[114:117], v[110:113], v[2:17]
	s_mov_b32 m0, s86
	s_waitcnt vmcnt(0) lgkmcnt(0)
	s_barrier
	ds_read_b128 v[102:105], v74 offset:16384
	ds_read_b128 v[106:109], v96
	ds_read_b128 v[110:113], v96 offset:4096
	ds_read_b128 v[114:117], v74 offset:20480
	v_mfma_f32_32x32x16_bf16 v[34:49], v[238:241], v[242:245], v[34:49]
	v_mfma_f32_32x32x16_bf16 v[18:33], v[238:241], v[246:249], v[18:33]
	v_lshl_add_u64 v[254:255], v[76:77], 0, s[36:37]
	global_load_lds_dwordx4 v[254:255], off
	v_lshl_add_u64 v[254:255], v[78:79], 0, s[36:37]
	s_mov_b32 m0, s87
	s_nop 0
	global_load_lds_dwordx4 v[254:255], off
	v_mfma_f32_32x32x16_bf16 v[50:65], v[250:253], v[242:245], v[50:65]
	v_lshl_add_u64 v[254:255], v[80:81], 0, s[36:37]
	s_mov_b32 m0, s88
	s_nop 0
	global_load_lds_dwordx4 v[254:255], off
	v_mfma_f32_32x32x16_bf16 v[2:17], v[250:253], v[246:249], v[2:17]
	s_waitcnt lgkmcnt(0)
	ds_read_b128 v[238:241], v95 offset:16384
	ds_read_b128 v[242:245], v97
	ds_read_b128 v[246:249], v97 offset:4096
	ds_read_b128 v[250:253], v95 offset:20480
	v_mfma_f32_32x32x16_bf16 v[34:49], v[102:105], v[106:109], v[34:49]
	v_lshl_add_u64 v[254:255], v[82:83], 0, s[36:37]
	s_mov_b32 m0, s89
	s_nop 0
	global_load_lds_dwordx4 v[254:255], off
	v_mfma_f32_32x32x16_bf16 v[18:33], v[102:105], v[110:113], v[18:33]
	v_lshl_add_u64 v[254:255], v[84:85], 0, s[36:37]
	s_mov_b32 m0, s91
	s_nop 0
	global_load_lds_dwordx4 v[254:255], off
	v_mfma_f32_32x32x16_bf16 v[50:65], v[114:117], v[106:109], v[50:65]
	v_mfma_f32_32x32x16_bf16 v[2:17], v[114:117], v[110:113], v[2:17]
	s_waitcnt lgkmcnt(0)
	ds_read_b128 v[102:105], v98 offset:16384
	ds_read_b128 v[106:109], v99
	ds_read_b128 v[110:113], v99 offset:4096
	ds_read_b128 v[114:117], v98 offset:20480
	v_mfma_f32_32x32x16_bf16 v[34:49], v[238:241], v[242:245], v[34:49]
	v_lshl_add_u64 v[254:255], v[86:87], 0, s[36:37]
	s_mov_b32 m0, s92
	s_nop 0
	global_load_lds_dwordx4 v[254:255], off
	v_mfma_f32_32x32x16_bf16 v[18:33], v[238:241], v[246:249], v[18:33]
	v_lshl_add_u64 v[254:255], v[88:89], 0, s[36:37]
	s_mov_b32 m0, s93
	s_nop 0
	global_load_lds_dwordx4 v[254:255], off
	v_mfma_f32_32x32x16_bf16 v[50:65], v[250:253], v[242:245], v[50:65]
	v_mfma_f32_32x32x16_bf16 v[2:17], v[250:253], v[246:249], v[2:17]
	s_waitcnt lgkmcnt(0)
	ds_read_b128 v[238:241], v100 offset:16384
	ds_read_b128 v[242:245], v101
	ds_read_b128 v[246:249], v101 offset:4096
	ds_read_b128 v[250:253], v100 offset:20480
	v_mfma_f32_32x32x16_bf16 v[34:49], v[102:105], v[106:109], v[34:49]
	v_lshl_add_u64 v[254:255], v[90:91], 0, s[36:37]
	s_mov_b32 m0, s94
	s_nop 0
	global_load_lds_dwordx4 v[254:255], off
	v_mfma_f32_32x32x16_bf16 v[18:33], v[102:105], v[110:113], v[18:33]
	v_mfma_f32_32x32x16_bf16 v[50:65], v[114:117], v[106:109], v[50:65]
	v_mfma_f32_32x32x16_bf16 v[2:17], v[114:117], v[110:113], v[2:17]
	s_mov_b32 m0, s1
	s_waitcnt vmcnt(0) lgkmcnt(0)
	s_barrier
; template <class Epi>
; DI void gemm_phase(const u16* __restrict__ A, const u16* __restrict__ B, int mtiles, int ntiles, char* lds, const Epi& epi) {
;     ...
;         for (int kt = 0; kt < 16; ++kt) {
;             if (kt + 1 < 16) GSTAGE((kt + 1) & 1, kt + 1, ga, gb);
;             const char* sa = lds + (kt & 1) * 32768; const char* sb = sa + 16384;
; #pragma unroll
;             for (int ks = 0; ks < 4; ++ks) {
;                 bf16x8 fw[2], fx[2];
; #pragma unroll
;                 for (int ct = 0; ct < 2; ++ct) fw[ct] = *(const bf16x8*)(sb + swz(wn * 64 + ct * 32 + r, 2 * ks + h));
; #pragma unroll
;                 for (int tt = 0; tt < 2; ++tt) fx[tt] = *(const bf16x8*)(sa + swz(wm * 64 + tt * 32 + r, 2 * ks + h));
; #pragma unroll
;                 for (int ct = 0; ct < 2; ++ct)
; #pragma unroll
;                     for (int tt = 0; tt < 2; ++tt) acc[ct][tt] = __builtin_amdgcn_mfma_f32_32x32x16_bf16(fw[ct], fx[tt], acc[ct][tt], 0, 0, 0);
;             }
;             __syncthreads();
;         }
	ds_read_b128 v[102:105], v74 offset:49152
	ds_read_b128 v[106:109], v96 offset:32768
	ds_read_b128 v[110:113], v96 offset:36864
	ds_read_b128 v[114:117], v74 offset:53248
	v_mfma_f32_32x32x16_bf16 v[34:49], v[238:241], v[242:245], v[34:49]
	v_mfma_f32_32x32x16_bf16 v[18:33], v[238:241], v[246:249], v[18:33]
	v_lshl_add_u64 v[254:255], v[76:77], 0, s[68:69]
	global_load_lds_dwordx4 v[254:255], off
	v_lshl_add_u64 v[254:255], v[78:79], 0, s[68:69]
	s_mov_b32 m0, s7
	v_lshl_add_u64 v[76:77], v[76:77], 0, s[70:71]
	global_load_lds_dwordx4 v[254:255], off
	v_mfma_f32_32x32x16_bf16 v[50:65], v[250:253], v[242:245], v[50:65]
	v_lshl_add_u64 v[254:255], v[80:81], 0, s[68:69]
	s_mov_b32 m0, s38
	s_nop 0
	global_load_lds_dwordx4 v[254:255], off
	v_mfma_f32_32x32x16_bf16 v[2:17], v[250:253], v[246:249], v[2:17]
	s_waitcnt lgkmcnt(0)
	ds_read_b128 v[238:241], v95 offset:49152
	ds_read_b128 v[242:245], v97 offset:32768
	ds_read_b128 v[246:249], v97 offset:36864
	ds_read_b128 v[250:253], v95 offset:53248
	v_mfma_f32_32x32x16_bf16 v[34:49], v[102:105], v[106:109], v[34:49]
	v_lshl_add_u64 v[254:255], v[82:83], 0, s[68:69]
	s_mov_b32 m0, s39
	s_nop 0
	global_load_lds_dwordx4 v[254:255], off
	v_mfma_f32_32x32x16_bf16 v[18:33], v[102:105], v[110:113], v[18:33]
	v_lshl_add_u64 v[254:255], v[84:85], 0, s[68:69]
	s_mov_b32 m0, s50
	s_nop 0
	global_load_lds_dwordx4 v[254:255], off
	v_mfma_f32_32x32x16_bf16 v[50:65], v[114:117], v[106:109], v[50:65]
	v_mfma_f32_32x32x16_bf16 v[2:17], v[114:117], v[110:113], v[2:17]
	s_waitcnt lgkmcnt(0)
	ds_read_b128 v[102:105], v98 offset:49152
	ds_read_b128 v[106:109], v99 offset:32768
	ds_read_b128 v[110:113], v99 offset:36864
	ds_read_b128 v[114:117], v98 offset:53248
	v_mfma_f32_32x32x16_bf16 v[34:49], v[238:241], v[242:245], v[34:49]
	v_lshl_add_u64 v[254:255], v[86:87], 0, s[68:69]
	s_mov_b32 m0, s51
	s_nop 0
	global_load_lds_dwordx4 v[254:255], off
	v_mfma_f32_32x32x16_bf16 v[18:33], v[238:241], v[246:249], v[18:33]
	v_lshl_add_u64 v[254:255], v[88:89], 0, s[68:69]
	s_mov_b32 m0, s83
	s_nop 0
	global_load_lds_dwordx4 v[254:255], off
	v_mfma_f32_32x32x16_bf16 v[50:65], v[250:253], v[242:245], v[50:65]
	v_mfma_f32_32x32x16_bf16 v[2:17], v[250:253], v[246:249], v[2:17]
	s_waitcnt lgkmcnt(0)
	ds_read_b128 v[238:241], v100 offset:49152
	ds_read_b128 v[242:245], v101 offset:32768
	ds_read_b128 v[246:249], v101 offset:36864
	ds_read_b128 v[250:253], v100 offset:53248
	v_mfma_f32_32x32x16_bf16 v[34:49], v[102:105], v[106:109], v[34:49]
	v_lshl_add_u64 v[254:255], v[90:91], 0, s[68:69]
	s_mov_b32 m0, s90
	s_nop 0
	global_load_lds_dwordx4 v[254:255], off
	v_mfma_f32_32x32x16_bf16 v[18:33], v[102:105], v[110:113], v[18:33]
	v_mfma_f32_32x32x16_bf16 v[50:65], v[114:117], v[106:109], v[50:65]
	v_mfma_f32_32x32x16_bf16 v[2:17], v[114:117], v[110:113], v[2:17]
	s_mov_b32 m0, s86
	s_mov_b32 s86, 0
	s_waitcnt vmcnt(0) lgkmcnt(0)
	s_barrier
	global_load_lds_dwordx4 v[76:77], off
	v_lshl_add_u64 v[76:77], v[78:79], 0, s[70:71]
	s_mov_b32 m0, s87
	v_mfma_f32_32x32x16_bf16 v[34:49], v[238:241], v[242:245], v[34:49]
	global_load_lds_dwordx4 v[76:77], off
	v_lshl_add_u64 v[76:77], v[80:81], 0, s[70:71]
	s_mov_b32 m0, s88
	s_mov_b32 s88, 0
	global_load_lds_dwordx4 v[76:77], off
	v_lshl_add_u64 v[76:77], v[82:83], 0, s[70:71]
	s_mov_b32 m0, s89
	v_mfma_f32_32x32x16_bf16 v[18:33], v[238:241], v[246:249], v[18:33]
	global_load_lds_dwordx4 v[76:77], off
	v_lshl_add_u64 v[76:77], v[84:85], 0, s[70:71]
	s_mov_b32 m0, s91
	s_nop 0
	global_load_lds_dwordx4 v[76:77], off
	v_lshl_add_u64 v[76:77], v[86:87], 0, s[70:71]
	s_mov_b32 m0, s92
	v_mfma_f32_32x32x16_bf16 v[50:65], v[250:253], v[242:245], v[50:65]
	global_load_lds_dwordx4 v[76:77], off
	v_lshl_add_u64 v[76:77], v[88:89], 0, s[70:71]
	s_mov_b32 m0, s93
	s_nop 0
	global_load_lds_dwordx4 v[76:77], off
	v_lshl_add_u64 v[76:77], v[90:91], 0, s[70:71]
	s_mov_b32 m0, s94
	v_mfma_f32_32x32x16_bf16 v[2:17], v[250:253], v[246:249], v[2:17]
	global_load_lds_dwordx4 v[76:77], off
	ds_read_b128 v[76:79], v74 offset:16384
	ds_read_b128 v[80:83], v96
	ds_read_b128 v[84:87], v96 offset:4096
	ds_read_b128 v[88:91], v74 offset:20480
	s_waitcnt lgkmcnt(0)
	v_mfma_f32_32x32x16_bf16 v[34:49], v[76:79], v[80:83], v[34:49]
	v_mfma_f32_32x32x16_bf16 v[18:33], v[76:79], v[84:87], v[18:33]
	v_mfma_f32_32x32x16_bf16 v[50:65], v[88:91], v[80:83], v[50:65]
	v_mfma_f32_32x32x16_bf16 v[2:17], v[88:91], v[84:87], v[2:17]
	ds_read_b128 v[76:79], v95 offset:16384
	ds_read_b128 v[80:83], v97
	ds_read_b128 v[84:87], v97 offset:4096
	ds_read_b128 v[88:91], v95 offset:20480
	s_waitcnt lgkmcnt(0)
	v_mfma_f32_32x32x16_bf16 v[34:49], v[76:79], v[80:83], v[34:49]
	v_mfma_f32_32x32x16_bf16 v[18:33], v[76:79], v[84:87], v[18:33]
	v_mfma_f32_32x32x16_bf16 v[50:65], v[88:91], v[80:83], v[50:65]
	v_mfma_f32_32x32x16_bf16 v[2:17], v[88:91], v[84:87], v[2:17]
	ds_read_b128 v[76:79], v98 offset:16384
	ds_read_b128 v[80:83], v99
	ds_read_b128 v[84:87], v99 offset:4096
	ds_read_b128 v[88:91], v98 offset:20480
	s_waitcnt lgkmcnt(0)
	v_mfma_f32_32x32x16_bf16 v[34:49], v[76:79], v[80:83], v[34:49]
	v_mfma_f32_32x32x16_bf16 v[18:33], v[76:79], v[84:87], v[18:33]
	v_mfma_f32_32x32x16_bf16 v[50:65], v[88:91], v[80:83], v[50:65]
	v_mfma_f32_32x32x16_bf16 v[2:17], v[88:91], v[84:87], v[2:17]
	ds_read_b128 v[76:79], v100 offset:16384
	ds_read_b128 v[80:83], v101
	ds_read_b128 v[84:87], v101 offset:4096
	ds_read_b128 v[88:91], v100 offset:20480
	s_waitcnt vmcnt(0) lgkmcnt(0)
	s_barrier
; #define TILE_MN(t, M0, N0) do { int pan_ = (t) / (mtiles * 8); if (pan_ >= npan) pan_ = npan - 1; const int pw_ = (pan_ == npan - 1) ? ntiles - 8 * pan_ : 8; const int loc_ = (t) - pan_ * mtiles * 8; \
;         M0 = (loc_ / pw_) * 128; N0 = (8 * pan_ + loc_ % pw_) * 128; } while (0)
; template <class Epi>
; DI void gemm_phase(const u16* __restrict__ A, const u16* __restrict__ B, int mtiles, int ntiles, char* lds, const Epi& epi) {
;     ...
;             for (int ks = 0; ks < 4; ++ks) {
;                 bf16x8 fw[2], fx[2];
; #pragma unroll
;                 for (int ct = 0; ct < 2; ++ct) fw[ct] = *(const bf16x8*)(sb + swz(wn * 64 + ct * 32 + r, 2 * ks + h));
; #pragma unroll
;                 for (int tt = 0; tt < 2; ++tt) fx[tt] = *(const bf16x8*)(sa + swz(wm * 64 + tt * 32 + r, 2 * ks + h));
; #pragma unroll
;                 for (int ct = 0; ct < 2; ++ct)
; #pragma unroll
;                     for (int tt = 0; tt < 2; ++tt) acc[ct][tt] = __builtin_amdgcn_mfma_f32_32x32x16_bf16(fw[ct], fx[tt], acc[ct][tt], 0, 0, 0);
;             }
;             __syncthreads();
;         }
;         const int nxt = tile + (int)gridDim.x; int m1 = 0, n1 = 0;
;         if (nxt < ntile) { TILE_MN(nxt, m1, n1); GSTAGE(0, 0, A + (size_t)m1 * 1024, B + (size_t)n1 * 1024); }
	v_mfma_f32_32x32x16_bf16 v[34:49], v[76:79], v[80:83], v[34:49]
	v_mfma_f32_32x32x16_bf16 v[18:33], v[76:79], v[84:87], v[18:33]
	v_mfma_f32_32x32x16_bf16 v[50:65], v[88:91], v[80:83], v[50:65]
	v_mfma_f32_32x32x16_bf16 v[2:17], v[88:91], v[84:87], v[2:17]
	ds_read_b128 v[76:79], v96 offset:32768
	ds_read_b128 v[80:83], v96 offset:36864
	ds_read_b128 v[84:87], v74 offset:49152
	ds_read_b128 v[88:91], v74 offset:53248
	s_waitcnt lgkmcnt(1)
	v_mfma_f32_32x32x16_bf16 v[34:49], v[84:87], v[76:79], v[34:49]
	v_mfma_f32_32x32x16_bf16 v[18:33], v[84:87], v[80:83], v[18:33]
	s_waitcnt lgkmcnt(0)
	v_mfma_f32_32x32x16_bf16 v[50:65], v[88:91], v[76:79], v[50:65]
	v_mfma_f32_32x32x16_bf16 v[2:17], v[88:91], v[80:83], v[2:17]
	ds_read_b128 v[76:79], v95 offset:49152
	ds_read_b128 v[80:83], v97 offset:32768
	ds_read_b128 v[84:87], v97 offset:36864
	ds_read_b128 v[88:91], v95 offset:53248
	s_waitcnt lgkmcnt(2)
	v_mfma_f32_32x32x16_bf16 v[34:49], v[76:79], v[80:83], v[34:49]
	s_waitcnt lgkmcnt(1)
	v_mfma_f32_32x32x16_bf16 v[18:33], v[76:79], v[84:87], v[18:33]
	s_waitcnt lgkmcnt(0)
	v_mfma_f32_32x32x16_bf16 v[50:65], v[88:91], v[80:83], v[50:65]
	v_mfma_f32_32x32x16_bf16 v[2:17], v[88:91], v[84:87], v[2:17]
	ds_read_b128 v[76:79], v98 offset:49152
	ds_read_b128 v[80:83], v99 offset:32768
	ds_read_b128 v[84:87], v99 offset:36864
	ds_read_b128 v[88:91], v98 offset:53248
	s_waitcnt lgkmcnt(2)
	v_mfma_f32_32x32x16_bf16 v[34:49], v[76:79], v[80:83], v[34:49]
	s_waitcnt lgkmcnt(1)
	v_mfma_f32_32x32x16_bf16 v[18:33], v[76:79], v[84:87], v[18:33]
	s_waitcnt lgkmcnt(0)
	v_mfma_f32_32x32x16_bf16 v[50:65], v[88:91], v[80:83], v[50:65]
	v_mfma_f32_32x32x16_bf16 v[2:17], v[88:91], v[84:87], v[2:17]
	ds_read_b128 v[76:79], v100 offset:49152
	ds_read_b128 v[80:83], v101 offset:32768
	ds_read_b128 v[84:87], v101 offset:36864
	ds_read_b128 v[88:91], v100 offset:53248
	s_waitcnt lgkmcnt(0)
	s_barrier
	v_mfma_f32_32x32x16_bf16 v[34:49], v[76:79], v[80:83], v[34:49]
	v_mfma_f32_32x32x16_bf16 v[18:33], v[76:79], v[84:87], v[18:33]
	v_mfma_f32_32x32x16_bf16 v[50:65], v[88:91], v[80:83], v[50:65]
	v_mfma_f32_32x32x16_bf16 v[2:17], v[88:91], v[84:87], v[2:17]
	s_cbranch_scc1 .LBB0_99
	s_mov_b32 m0, s1
	s_mul_hi_i32 s1, s33, 0x3e0f83e1
	s_lshr_b32 s86, s1, 31
	s_ashr_i32 s1, s1, 8
	s_add_i32 s1, s1, s86
	s_cmpk_lt_i32 s33, 0x1080
	s_cselect_b32 s1, s1, 3
	s_cmp_eq_u32 s1, 3
	s_cselect_b32 s87, 9, 8
	v_cvt_f32_ubyte0_e32 v74, s87
	v_rcp_iflag_f32_e32 v74, v74
	s_sub_i32 s91, 0, s87
	s_mul_i32 s86, s1, 0xfffffbe0
	s_add_i32 s88, s33, s86
	v_mul_f32_e32 v74, 0x4f7ffffe, v74
	v_cvt_u32_f32_e32 v74, v74
	s_abs_i32 s89, s88
	s_ashr_i32 s86, s88, 31
	v_readfirstlane_b32 s92, v74
	s_mul_i32 s91, s91, s92
	s_mul_hi_u32 s91, s92, s91
	s_add_i32 s92, s92, s91
	s_mul_hi_u32 s91, s89, s92
	s_mul_i32 s92, s91, s87
	s_sub_i32 s89, s89, s92
	s_add_i32 s92, s91, 1
	s_sub_i32 s93, s89, s87
	s_cmp_ge_u32 s89, s87
	s_cselect_b32 s91, s92, s91
	s_cselect_b32 s89, s93, s89
	s_add_i32 s92, s91, 1
	s_cmp_ge_u32 s89, s87
	s_cselect_b32 s89, s92, s91
	s_xor_b32 s89, s89, s86
	s_sub_i32 s89, s89, s86
	s_lshl_b32 s86, s89, 7
	s_mul_i32 s89, s89, s87
	s_sub_i32 s87, s88, s89
	s_lshl_b32 s1, s1, 10
	s_lshl_b32 s87, s87, 7
	s_add_i32 s88, s87, s1
	s_ashr_i32 s87, s86, 31
	s_lshl_b64 s[92:93], s[86:87], 11
	s_add_u32 s92, s54, s92
	s_addc_u32 s93, s55, s93
	s_ashr_i32 s89, s88, 31
	s_lshl_b64 s[94:95], s[88:89], 11
	v_readlane_b32 s1, v236, 9
	s_add_u32 s94, s1, s94
	v_readlane_b32 s1, v236, 11
	s_addc_u32 s95, s1, s95
	v_lshl_add_u64 v[76:77], s[92:93], 0, v[66:67]
	global_load_lds_dwordx4 v[76:77], off
	v_lshl_add_u64 v[66:67], s[94:95], 0, v[66:67]
	s_mov_b32 m0, s7
	s_nop 0
	global_load_lds_dwordx4 v[66:67], off
	v_lshl_add_u64 v[66:67], s[92:93], 0, v[68:69]
	s_mov_b32 m0, s38
	s_nop 0
	global_load_lds_dwordx4 v[66:67], off
	v_lshl_add_u64 v[66:67], s[94:95], 0, v[68:69]
	s_mov_b32 m0, s39
	s_nop 0
	global_load_lds_dwordx4 v[66:67], off
	v_lshl_add_u64 v[66:67], s[92:93], 0, v[70:71]
	s_mov_b32 m0, s50
	s_nop 0
	global_load_lds_dwordx4 v[66:67], off
	v_lshl_add_u64 v[66:67], s[94:95], 0, v[70:71]
	s_mov_b32 m0, s51
	s_nop 0
	global_load_lds_dwordx4 v[66:67], off
	v_lshl_add_u64 v[66:67], s[92:93], 0, v[72:73]
	s_mov_b32 m0, s83
	s_nop 0
	global_load_lds_dwordx4 v[66:67], off
	v_lshl_add_u64 v[66:67], s[94:95], 0, v[72:73]
	s_mov_b32 m0, s90
	s_nop 0
	global_load_lds_dwordx4 v[66:67], off

; DI void gemm_out(const Params& p, char* lds) {
;     ...
;     for (int tile = vb; tile < ntile; tile += gridDim.x) {
;         int tid = threadIdx.x; asm volatile("" : "+v"(tid));
;         const int lane = tid & 63, wave = __builtin_amdgcn_readfirstlane(tid >> 6); const int wn = wave >> 1, wm = wave & 1; const int q = lane & 15, g = lane >> 4;
;         const int mt = tile >> 3, nt = tile & 7; const int m0 = mt * 96, n0 = nt * 128;
;         f32x4 acc[4][3];
; #pragma unroll
;         for (int a = 0; a < 4; ++a)
; #pragma unroll
;             for (int b = 0; b < 3; ++b) acc[a][b] = (f32x4){0.f, 0.f, 0.f, 0.f};
;         unsigned soffb[4], soffa[3];
; #pragma unroll
;         for (int i = 0; i < 4; ++i) { const int row = 8 * (i * 4 + wave) + (lane >> 3); const int ch = (lane & 7) ^ ((row >> 1) & 7); soffb[i] = (unsigned)(row * 1024 + ch * 8); }
; #pragma unroll
;         for (int i = 0; i < 3; ++i) { const int row = 8 * (i * 4 + wave) + (lane >> 3); const int ch = (lane & 7) ^ ((row >> 1) & 7); soffa[i] = (unsigned)(row * 1024 + ch * 8); }
;         const u16* ga = A + (size_t)m0 * 1024; const u16* gb = B + (size_t)n0 * 1024;
;     ...
;         OSTAGE(0, 0);
;         float4 xres[3][4];
; #pragma unroll
;         for (int tt = 0; tt < 3; ++tt) { const int row = m0 + wm * 48 + tt * 16 + q; const float* xr = row < NTP ? p.x_p + (size_t)row * DM : p.x_s + (size_t)(row - NTP) * DM;
; #pragma unroll
;             for (int ct = 0; ct < 4; ++ct) xres[tt][ct] = ntld4(xr + n0 + wn * 64 + ct * 16 + 4 * g); }
;         __syncthreads();
;         for (int kt = 0; kt < 16; ++kt) {
;             if (kt + 1 < 16) OSTAGE((kt + 1) & 1, kt + 1);
;             const char* sb = lds + (kt & 1) * 28672; const char* sa = sb + 16384;
; #pragma unroll
;             for (int ks = 0; ks < 2; ++ks) {
;                 bf16x8 fw[4], fx[3];
; #pragma unroll
;                 for (int ct = 0; ct < 4; ++ct) fw[ct] = *(const bf16x8*)(sb + swz(wn * 64 + ct * 16 + q, 4 * ks + g));
; #pragma unroll
;                 for (int tt = 0; tt < 3; ++tt) fx[tt] = *(const bf16x8*)(sa + swz(wm * 48 + tt * 16 + q, 4 * ks + g));
; #pragma unroll
;                 for (int ct = 0; ct < 4; ++ct)
; #pragma unroll
;                     for (int tt = 0; tt < 3; ++tt) acc[ct][tt] = __builtin_amdgcn_mfma_f32_16x16x32_bf16(fw[ct], fx[tt], acc[ct][tt], 0, 0, 0);
;             }
;             __syncthreads();
;         }
.Lo_tile:
	v_mov_b32_e32 v18, v0
	s_ashr_i32 s83, s82, 31
	v_readfirstlane_b32 s1, v18
	s_ashr_i32 s7, s1, 6
	s_ashr_i32 s4, s1, 7
	s_and_b32 s6, s7, 1
	v_bfe_u32 v2, v18, 3, 3
	s_lshl_b64 s[38:39], s[82:83], 11
	v_lshl_or_b32 v2, s7, 3, v2
	s_add_u32 s38, s54, s38
	v_lshrrev_b32_e32 v3, 1, v2
	s_addc_u32 s39, s55, s39
	s_ashr_i32 s1, s0, 31
	v_xor_b32_e32 v3, v3, v18
	s_lshl_b64 s[50:51], s[0:1], 11
	v_readlane_b32 s1, v236, 9
	v_lshlrev_b32_e32 v2, 10, v2
	v_lshlrev_b32_e32 v3, 3, v3
	s_add_u32 s50, s1, s50
	v_readlane_b32 s1, v236, 11
	v_and_or_b32 v74, v3, 56, v2
	s_addc_u32 s51, s1, s51
	s_lshl_b32 s1, s7, 10
	v_lshlrev_b64 v[66:67], 1, v[74:75]
	s_add_i32 s1, s1, 0
	v_add_u32_e32 v2, 0x8000, v74
	v_bfe_u32 v93, v18, 5, 1
	v_lshrrev_b32_e32 v8, 1, v18
	v_mov_b32_e32 v3, v75
	v_lshl_add_u64 v[76:77], s[38:39], 0, v[66:67]
	s_add_i32 s86, s1, 0x8000
	v_bitop3_b32 v10, v93, v8, 7 bitop3:0x78
	v_lshl_add_u64 v[8:9], v[76:77], 0, s[8:9]
	s_mov_b32 m0, s86
	v_lshl_add_u64 v[78:79], s[50:51], 0, v[66:67]
	s_add_i32 s87, s1, 0xc000
	v_lshlrev_b64 v[68:69], 1, v[2:3]
	v_add_u32_e32 v4, 0x10000, v74
	s_waitcnt vmcnt(0) lgkmcnt(0)
	s_barrier
	v_mov_b32_e32 v5, v75
	global_load_lds_dwordx4 v[8:9], off
	v_lshl_add_u64 v[8:9], v[78:79], 0, s[8:9]
	s_mov_b32 m0, s87
	v_lshl_add_u64 v[80:81], s[38:39], 0, v[68:69]
	s_add_i32 s88, s1, 0x9000
	global_load_lds_dwordx4 v[8:9], off
	v_lshl_add_u64 v[2:3], v[80:81], 0, s[8:9]
	s_mov_b32 m0, s88
	v_lshl_add_u64 v[82:83], s[50:51], 0, v[68:69]
	s_add_i32 s89, s1, 0xd000
	v_lshlrev_b64 v[70:71], 1, v[4:5]
	v_add_u32_e32 v6, 0x18000, v74
	v_mov_b32_e32 v7, v75
	global_load_lds_dwordx4 v[2:3], off
	v_lshl_add_u64 v[2:3], v[82:83], 0, s[8:9]
	s_mov_b32 m0, s89
	v_lshl_add_u64 v[84:85], s[38:39], 0, v[70:71]
	s_add_i32 s91, s1, 0xa000
	global_load_lds_dwordx4 v[2:3], off
	v_lshl_add_u64 v[2:3], v[84:85], 0, s[8:9]
	s_mov_b32 m0, s91
	v_lshl_add_u64 v[86:87], s[50:51], 0, v[70:71]
	s_add_i32 s92, s1, 0xe000
	v_lshlrev_b64 v[72:73], 1, v[6:7]
	global_load_lds_dwordx4 v[2:3], off
	v_lshl_add_u64 v[2:3], v[86:87], 0, s[8:9]
	s_mov_b32 m0, s92
	v_lshl_add_u64 v[88:89], s[38:39], 0, v[72:73]
	s_add_i32 s93, s1, 0xb000
	v_and_b32_e32 v94, 31, v18
	global_load_lds_dwordx4 v[2:3], off
	v_lshl_add_u64 v[2:3], v[88:89], 0, s[8:9]
	s_mov_b32 m0, s93
	v_lshl_add_u64 v[90:91], s[50:51], 0, v[72:73]
	s_add_i32 s94, s1, 0xf000
	s_lshl_b32 s7, s4, 13
	v_lshlrev_b32_e32 v116, 7, v94
	global_load_lds_dwordx4 v[2:3], off
	v_lshl_add_u64 v[2:3], v[90:91], 0, s[8:9]
	s_mov_b32 m0, s94
	v_lshl_add_u32 v6, v10, 4, 0
	global_load_lds_dwordx4 v[2:3], off
	v_add3_u32 v74, v6, s7, v116
	ds_read_b128 v[2:5], v74 offset:16384
	s_lshl_b32 s38, s6, 13
	v_add3_u32 v96, v6, s38, v116
	v_bfe_u32 v117, v18, 1, 3
	ds_read_b128 v[6:9], v96
	ds_read_b128 v[10:13], v96 offset:4096
	ds_read_b128 v[14:17], v74 offset:20480
	v_bitop3_b32 v18, v93, v117, 2 bitop3:0x36
	v_lshl_add_u32 v18, v18, 4, 0
	v_add3_u32 v95, v18, s7, v116
	ds_read_b128 v[50:53], v95 offset:16384
	s_waitcnt lgkmcnt(0)
	v_mfma_f32_32x32x16_bf16 v[34:49], v[6:9], v[2:5], 0
	v_add3_u32 v97, v18, s38, v116
	ds_read_b128 v[98:101], v97
	ds_read_b128 v[102:105], v97 offset:4096
	ds_read_b128 v[106:109], v95 offset:20480
	s_mov_b32 m0, s1
	s_add_i32 s39, s1, 0x5000
	s_add_i32 s50, s1, 0x2000
	s_add_i32 s51, s1, 0x6000
	s_add_i32 s83, s1, 0x3000
	v_mfma_f32_32x32x16_bf16 v[18:33], v[10:13], v[2:5], 0
	s_add_i32 s90, s1, 0x7000
	s_add_i32 s33, s33, s95
	s_waitcnt lgkmcnt(0)
	v_mfma_f32_32x32x16_bf16 v[34:49], v[98:101], v[50:53], v[34:49]
	v_mfma_f32_32x32x16_bf16 v[18:33], v[102:105], v[50:53], v[18:33]
	v_mfma_f32_32x32x16_bf16 v[50:65], v[6:9], v[14:17], 0
	v_mfma_f32_32x32x16_bf16 v[2:17], v[10:13], v[14:17], 0
	v_mfma_f32_32x32x16_bf16 v[50:65], v[98:101], v[106:109], v[50:65]
	v_bitop3_b32 v98, v93, v117, 4 bitop3:0x36
	v_lshl_add_u32 v99, v98, 4, 0
	v_add3_u32 v98, v99, s7, v116
	v_add3_u32 v99, v99, s38, v116
	v_mfma_f32_32x32x16_bf16 v[2:17], v[102:105], v[106:109], v[2:17]
	ds_read_b128 v[100:103], v98 offset:16384
	ds_read_b128 v[104:107], v99
	ds_read_b128 v[108:111], v99 offset:4096
	ds_read_b128 v[112:115], v98 offset:20480
	s_waitcnt lgkmcnt(0)
	v_mfma_f32_32x32x16_bf16 v[34:49], v[104:107], v[100:103], v[34:49]
	v_mfma_f32_32x32x16_bf16 v[18:33], v[108:111], v[100:103], v[18:33]
	v_bitop3_b32 v100, v93, v117, 6 bitop3:0x36
	v_lshl_add_u32 v101, v100, 4, 0
	v_add3_u32 v100, v101, s7, v116
	v_add3_u32 v101, v101, s38, v116
	s_add_i32 s7, s1, 0x4000
	s_add_i32 s38, s1, 0x1000
	s_cmpk_gt_i32 s33, 0x41f
	v_mfma_f32_32x32x16_bf16 v[50:65], v[104:107], v[112:115], v[50:65]
	v_mfma_f32_32x32x16_bf16 v[2:17], v[108:111], v[112:115], v[2:17]
	ds_read_b128 v[238:241], v100 offset:16384
	ds_read_b128 v[242:245], v101
	ds_read_b128 v[246:249], v101 offset:4096
	ds_read_b128 v[250:253], v100 offset:20480
	s_waitcnt vmcnt(0) lgkmcnt(0)
	s_barrier
; DI void gemm_out(const Params& p, char* lds) {
;     ...
;         for (int kt = 0; kt < 16; ++kt) {
;             if (kt + 1 < 16) OSTAGE((kt + 1) & 1, kt + 1);
;             const char* sb = lds + (kt & 1) * 28672; const char* sa = sb + 16384;
; #pragma unroll
;             for (int ks = 0; ks < 2; ++ks) {
;                 bf16x8 fw[4], fx[3];
; #pragma unroll
;                 for (int ct = 0; ct < 4; ++ct) fw[ct] = *(const bf16x8*)(sb + swz(wn * 64 + ct * 16 + q, 4 * ks + g));
; #pragma unroll
;                 for (int tt = 0; tt < 3; ++tt) fx[tt] = *(const bf16x8*)(sa + swz(wm * 48 + tt * 16 + q, 4 * ks + g));
; #pragma unroll
;                 for (int ct = 0; ct < 4; ++ct)
; #pragma unroll
;                     for (int tt = 0; tt < 3; ++tt) acc[ct][tt] = __builtin_amdgcn_mfma_f32_16x16x32_bf16(fw[ct], fx[tt], acc[ct][tt], 0, 0, 0);
;             }
;             __syncthreads();
;         }
	ds_read_b128 v[102:105], v74 offset:49152
	ds_read_b128 v[106:109], v96 offset:32768
	ds_read_b128 v[110:113], v96 offset:36864
	ds_read_b128 v[114:117], v74 offset:53248
	v_mfma_f32_32x32x16_bf16 v[34:49], v[242:245], v[238:241], v[34:49]
	v_mfma_f32_32x32x16_bf16 v[18:33], v[246:249], v[238:241], v[18:33]
	v_lshl_add_u64 v[254:255], v[76:77], 0, s[10:11]
	global_load_lds_dwordx4 v[254:255], off
	v_lshl_add_u64 v[254:255], v[78:79], 0, s[10:11]
	s_mov_b32 m0, s7
	s_nop 0
	global_load_lds_dwordx4 v[254:255], off
	v_mfma_f32_32x32x16_bf16 v[50:65], v[242:245], v[250:253], v[50:65]
	v_lshl_add_u64 v[254:255], v[80:81], 0, s[10:11]
	s_mov_b32 m0, s38
	s_nop 0
	global_load_lds_dwordx4 v[254:255], off
	v_mfma_f32_32x32x16_bf16 v[2:17], v[246:249], v[250:253], v[2:17]
	s_waitcnt lgkmcnt(0)
	ds_read_b128 v[238:241], v95 offset:49152
	ds_read_b128 v[242:245], v97 offset:32768
	ds_read_b128 v[246:249], v97 offset:36864
	ds_read_b128 v[250:253], v95 offset:53248
	v_mfma_f32_32x32x16_bf16 v[34:49], v[106:109], v[102:105], v[34:49]
	v_lshl_add_u64 v[254:255], v[82:83], 0, s[10:11]
	s_mov_b32 m0, s39
	s_nop 0
	global_load_lds_dwordx4 v[254:255], off
	v_mfma_f32_32x32x16_bf16 v[18:33], v[110:113], v[102:105], v[18:33]
	v_lshl_add_u64 v[254:255], v[84:85], 0, s[10:11]
	s_mov_b32 m0, s50
	s_nop 0
	global_load_lds_dwordx4 v[254:255], off
	v_mfma_f32_32x32x16_bf16 v[50:65], v[106:109], v[114:117], v[50:65]
	v_mfma_f32_32x32x16_bf16 v[2:17], v[110:113], v[114:117], v[2:17]
	s_waitcnt lgkmcnt(0)
	ds_read_b128 v[102:105], v98 offset:49152
	ds_read_b128 v[106:109], v99 offset:32768
	ds_read_b128 v[110:113], v99 offset:36864
	ds_read_b128 v[114:117], v98 offset:53248
	v_mfma_f32_32x32x16_bf16 v[34:49], v[242:245], v[238:241], v[34:49]
	v_lshl_add_u64 v[254:255], v[86:87], 0, s[10:11]
	s_mov_b32 m0, s51
	s_nop 0
	global_load_lds_dwordx4 v[254:255], off
	v_mfma_f32_32x32x16_bf16 v[18:33], v[246:249], v[238:241], v[18:33]
	v_lshl_add_u64 v[254:255], v[88:89], 0, s[10:11]
	s_mov_b32 m0, s83
	s_nop 0
	global_load_lds_dwordx4 v[254:255], off
	v_mfma_f32_32x32x16_bf16 v[50:65], v[242:245], v[250:253], v[50:65]
	v_mfma_f32_32x32x16_bf16 v[2:17], v[246:249], v[250:253], v[2:17]
	s_waitcnt lgkmcnt(0)
	ds_read_b128 v[238:241], v100 offset:49152
	ds_read_b128 v[242:245], v101 offset:32768
	ds_read_b128 v[246:249], v101 offset:36864
	ds_read_b128 v[250:253], v100 offset:53248
	v_mfma_f32_32x32x16_bf16 v[34:49], v[106:109], v[102:105], v[34:49]
	v_lshl_add_u64 v[254:255], v[90:91], 0, s[10:11]
	s_mov_b32 m0, s90
	s_nop 0
	global_load_lds_dwordx4 v[254:255], off
	v_mfma_f32_32x32x16_bf16 v[18:33], v[110:113], v[102:105], v[18:33]
	v_mfma_f32_32x32x16_bf16 v[50:65], v[106:109], v[114:117], v[50:65]
	v_mfma_f32_32x32x16_bf16 v[2:17], v[110:113], v[114:117], v[2:17]
	s_mov_b32 m0, s86
	s_waitcnt vmcnt(0) lgkmcnt(0)
	s_barrier
	ds_read_b128 v[102:105], v74 offset:16384
	ds_read_b128 v[106:109], v96
	ds_read_b128 v[110:113], v96 offset:4096
	ds_read_b128 v[114:117], v74 offset:20480
	v_mfma_f32_32x32x16_bf16 v[34:49], v[242:245], v[238:241], v[34:49]
	v_mfma_f32_32x32x16_bf16 v[18:33], v[246:249], v[238:241], v[18:33]
	v_lshl_add_u64 v[254:255], v[76:77], 0, s[12:13]
	global_load_lds_dwordx4 v[254:255], off
	v_lshl_add_u64 v[254:255], v[78:79], 0, s[12:13]
	s_mov_b32 m0, s87
	s_nop 0
	global_load_lds_dwordx4 v[254:255], off
	v_mfma_f32_32x32x16_bf16 v[50:65], v[242:245], v[250:253], v[50:65]
	v_lshl_add_u64 v[254:255], v[80:81], 0, s[12:13]
	s_mov_b32 m0, s88
	s_nop 0
	global_load_lds_dwordx4 v[254:255], off
	v_mfma_f32_32x32x16_bf16 v[2:17], v[246:249], v[250:253], v[2:17]
	s_waitcnt lgkmcnt(0)
	ds_read_b128 v[238:241], v95 offset:16384
	ds_read_b128 v[242:245], v97
	ds_read_b128 v[246:249], v97 offset:4096
	ds_read_b128 v[250:253], v95 offset:20480
	v_mfma_f32_32x32x16_bf16 v[34:49], v[106:109], v[102:105], v[34:49]
	v_lshl_add_u64 v[254:255], v[82:83], 0, s[12:13]
	s_mov_b32 m0, s89
	s_nop 0
	global_load_lds_dwordx4 v[254:255], off
	v_mfma_f32_32x32x16_bf16 v[18:33], v[110:113], v[102:105], v[18:33]
	v_lshl_add_u64 v[254:255], v[84:85], 0, s[12:13]
	s_mov_b32 m0, s91
	s_nop 0
	global_load_lds_dwordx4 v[254:255], off
	v_mfma_f32_32x32x16_bf16 v[50:65], v[106:109], v[114:117], v[50:65]
	v_mfma_f32_32x32x16_bf16 v[2:17], v[110:113], v[114:117], v[2:17]
	s_waitcnt lgkmcnt(0)
	ds_read_b128 v[102:105], v98 offset:16384
	ds_read_b128 v[106:109], v99
	ds_read_b128 v[110:113], v99 offset:4096
	ds_read_b128 v[114:117], v98 offset:20480
	v_mfma_f32_32x32x16_bf16 v[34:49], v[242:245], v[238:241], v[34:49]
	v_lshl_add_u64 v[254:255], v[86:87], 0, s[12:13]
	s_mov_b32 m0, s92
	s_nop 0
	global_load_lds_dwordx4 v[254:255], off
	v_mfma_f32_32x32x16_bf16 v[18:33], v[246:249], v[238:241], v[18:33]
	v_lshl_add_u64 v[254:255], v[88:89], 0, s[12:13]
	s_mov_b32 m0, s93
	s_nop 0
	global_load_lds_dwordx4 v[254:255], off
	v_mfma_f32_32x32x16_bf16 v[50:65], v[242:245], v[250:253], v[50:65]
	v_mfma_f32_32x32x16_bf16 v[2:17], v[246:249], v[250:253], v[2:17]
	s_waitcnt lgkmcnt(0)
	ds_read_b128 v[238:241], v100 offset:16384
	ds_read_b128 v[242:245], v101
	ds_read_b128 v[246:249], v101 offset:4096
	ds_read_b128 v[250:253], v100 offset:20480
	v_mfma_f32_32x32x16_bf16 v[34:49], v[106:109], v[102:105], v[34:49]
	v_lshl_add_u64 v[254:255], v[90:91], 0, s[12:13]
	s_mov_b32 m0, s94
	s_nop 0
	global_load_lds_dwordx4 v[254:255], off
	v_mfma_f32_32x32x16_bf16 v[18:33], v[110:113], v[102:105], v[18:33]
	v_mfma_f32_32x32x16_bf16 v[50:65], v[106:109], v[114:117], v[50:65]
	v_mfma_f32_32x32x16_bf16 v[2:17], v[110:113], v[114:117], v[2:17]
	s_mov_b32 m0, s1
	s_waitcnt vmcnt(0) lgkmcnt(0)
	s_barrier
; DI void gemm_out(const Params& p, char* lds) {
;     ...
;         for (int kt = 0; kt < 16; ++kt) {
;             if (kt + 1 < 16) OSTAGE((kt + 1) & 1, kt + 1);
;             const char* sb = lds + (kt & 1) * 28672; const char* sa = sb + 16384;
; #pragma unroll
;             for (int ks = 0; ks < 2; ++ks) {
;                 bf16x8 fw[4], fx[3];
; #pragma unroll
;                 for (int ct = 0; ct < 4; ++ct) fw[ct] = *(const bf16x8*)(sb + swz(wn * 64 + ct * 16 + q, 4 * ks + g));
; #pragma unroll
;                 for (int tt = 0; tt < 3; ++tt) fx[tt] = *(const bf16x8*)(sa + swz(wm * 48 + tt * 16 + q, 4 * ks + g));
; #pragma unroll
;                 for (int ct = 0; ct < 4; ++ct)
; #pragma unroll
;                     for (int tt = 0; tt < 3; ++tt) acc[ct][tt] = __builtin_amdgcn_mfma_f32_16x16x32_bf16(fw[ct], fx[tt], acc[ct][tt], 0, 0, 0);
;             }
;             __syncthreads();
;         }
	ds_read_b128 v[102:105], v74 offset:49152
	ds_read_b128 v[106:109], v96 offset:32768
	ds_read_b128 v[110:113], v96 offset:36864
	ds_read_b128 v[114:117], v74 offset:53248
	v_mfma_f32_32x32x16_bf16 v[34:49], v[242:245], v[238:241], v[34:49]
	v_mfma_f32_32x32x16_bf16 v[18:33], v[246:249], v[238:241], v[18:33]
	v_lshl_add_u64 v[254:255], v[76:77], 0, s[14:15]
	global_load_lds_dwordx4 v[254:255], off
	v_lshl_add_u64 v[254:255], v[78:79], 0, s[14:15]
	s_mov_b32 m0, s7
	s_nop 0
	global_load_lds_dwordx4 v[254:255], off
	v_mfma_f32_32x32x16_bf16 v[50:65], v[242:245], v[250:253], v[50:65]
	v_lshl_add_u64 v[254:255], v[80:81], 0, s[14:15]
	s_mov_b32 m0, s38
	s_nop 0
	global_load_lds_dwordx4 v[254:255], off
	v_mfma_f32_32x32x16_bf16 v[2:17], v[246:249], v[250:253], v[2:17]
	s_waitcnt lgkmcnt(0)
	ds_read_b128 v[238:241], v95 offset:49152
	ds_read_b128 v[242:245], v97 offset:32768
	ds_read_b128 v[246:249], v97 offset:36864
	ds_read_b128 v[250:253], v95 offset:53248
	v_mfma_f32_32x32x16_bf16 v[34:49], v[106:109], v[102:105], v[34:49]
	v_lshl_add_u64 v[254:255], v[82:83], 0, s[14:15]
	s_mov_b32 m0, s39
	s_nop 0
	global_load_lds_dwordx4 v[254:255], off
	v_mfma_f32_32x32x16_bf16 v[18:33], v[110:113], v[102:105], v[18:33]
	v_lshl_add_u64 v[254:255], v[84:85], 0, s[14:15]
	s_mov_b32 m0, s50
	s_nop 0
	global_load_lds_dwordx4 v[254:255], off
	v_mfma_f32_32x32x16_bf16 v[50:65], v[106:109], v[114:117], v[50:65]
	v_mfma_f32_32x32x16_bf16 v[2:17], v[110:113], v[114:117], v[2:17]
	s_waitcnt lgkmcnt(0)
	ds_read_b128 v[102:105], v98 offset:49152
	ds_read_b128 v[106:109], v99 offset:32768
	ds_read_b128 v[110:113], v99 offset:36864
	ds_read_b128 v[114:117], v98 offset:53248
	v_mfma_f32_32x32x16_bf16 v[34:49], v[242:245], v[238:241], v[34:49]
	v_lshl_add_u64 v[254:255], v[86:87], 0, s[14:15]
	s_mov_b32 m0, s51
	s_nop 0
	global_load_lds_dwordx4 v[254:255], off
	v_mfma_f32_32x32x16_bf16 v[18:33], v[246:249], v[238:241], v[18:33]
	v_lshl_add_u64 v[254:255], v[88:89], 0, s[14:15]
	s_mov_b32 m0, s83
	s_nop 0
	global_load_lds_dwordx4 v[254:255], off
	v_mfma_f32_32x32x16_bf16 v[50:65], v[242:245], v[250:253], v[50:65]
	v_mfma_f32_32x32x16_bf16 v[2:17], v[246:249], v[250:253], v[2:17]
	s_waitcnt lgkmcnt(0)
	ds_read_b128 v[238:241], v100 offset:49152
	ds_read_b128 v[242:245], v101 offset:32768
	ds_read_b128 v[246:249], v101 offset:36864
	ds_read_b128 v[250:253], v100 offset:53248
	v_mfma_f32_32x32x16_bf16 v[34:49], v[106:109], v[102:105], v[34:49]
	v_lshl_add_u64 v[254:255], v[90:91], 0, s[14:15]
	s_mov_b32 m0, s90
	s_nop 0
	global_load_lds_dwordx4 v[254:255], off
	v_mfma_f32_32x32x16_bf16 v[18:33], v[110:113], v[102:105], v[18:33]
	v_mfma_f32_32x32x16_bf16 v[50:65], v[106:109], v[114:117], v[50:65]
	v_mfma_f32_32x32x16_bf16 v[2:17], v[110:113], v[114:117], v[2:17]
	s_mov_b32 m0, s86
	s_waitcnt vmcnt(0) lgkmcnt(0)
	s_barrier
	ds_read_b128 v[102:105], v74 offset:16384
	ds_read_b128 v[106:109], v96
	ds_read_b128 v[110:113], v96 offset:4096
	ds_read_b128 v[114:117], v74 offset:20480
	v_mfma_f32_32x32x16_bf16 v[34:49], v[242:245], v[238:241], v[34:49]
	v_mfma_f32_32x32x16_bf16 v[18:33], v[246:249], v[238:241], v[18:33]
	v_lshl_add_u64 v[254:255], v[76:77], 0, s[16:17]
	global_load_lds_dwordx4 v[254:255], off
	v_lshl_add_u64 v[254:255], v[78:79], 0, s[16:17]
	s_mov_b32 m0, s87
	s_nop 0
	global_load_lds_dwordx4 v[254:255], off
	v_mfma_f32_32x32x16_bf16 v[50:65], v[242:245], v[250:253], v[50:65]
	v_lshl_add_u64 v[254:255], v[80:81], 0, s[16:17]
	s_mov_b32 m0, s88
	s_nop 0
	global_load_lds_dwordx4 v[254:255], off
	v_mfma_f32_32x32x16_bf16 v[2:17], v[246:249], v[250:253], v[2:17]
	s_waitcnt lgkmcnt(0)
	ds_read_b128 v[238:241], v95 offset:16384
	ds_read_b128 v[242:245], v97
	ds_read_b128 v[246:249], v97 offset:4096
	ds_read_b128 v[250:253], v95 offset:20480
	v_mfma_f32_32x32x16_bf16 v[34:49], v[106:109], v[102:105], v[34:49]
	v_lshl_add_u64 v[254:255], v[82:83], 0, s[16:17]
	s_mov_b32 m0, s89
	s_nop 0
	global_load_lds_dwordx4 v[254:255], off
	v_mfma_f32_32x32x16_bf16 v[18:33], v[110:113], v[102:105], v[18:33]
	v_lshl_add_u64 v[254:255], v[84:85], 0, s[16:17]
	s_mov_b32 m0, s91
	s_nop 0
	global_load_lds_dwordx4 v[254:255], off
	v_mfma_f32_32x32x16_bf16 v[50:65], v[106:109], v[114:117], v[50:65]
	v_mfma_f32_32x32x16_bf16 v[2:17], v[110:113], v[114:117], v[2:17]
	s_waitcnt lgkmcnt(0)
	ds_read_b128 v[102:105], v98 offset:16384
	ds_read_b128 v[106:109], v99
	ds_read_b128 v[110:113], v99 offset:4096
	ds_read_b128 v[114:117], v98 offset:20480
	v_mfma_f32_32x32x16_bf16 v[34:49], v[242:245], v[238:241], v[34:49]
	v_lshl_add_u64 v[254:255], v[86:87], 0, s[16:17]
	s_mov_b32 m0, s92
	s_nop 0
	global_load_lds_dwordx4 v[254:255], off
	v_mfma_f32_32x32x16_bf16 v[18:33], v[246:249], v[238:241], v[18:33]
	v_lshl_add_u64 v[254:255], v[88:89], 0, s[16:17]
	s_mov_b32 m0, s93
	s_nop 0
	global_load_lds_dwordx4 v[254:255], off
	v_mfma_f32_32x32x16_bf16 v[50:65], v[242:245], v[250:253], v[50:65]
	v_mfma_f32_32x32x16_bf16 v[2:17], v[246:249], v[250:253], v[2:17]
	s_waitcnt lgkmcnt(0)
	ds_read_b128 v[238:241], v100 offset:16384
	ds_read_b128 v[242:245], v101
	ds_read_b128 v[246:249], v101 offset:4096
	ds_read_b128 v[250:253], v100 offset:20480
	v_mfma_f32_32x32x16_bf16 v[34:49], v[106:109], v[102:105], v[34:49]
	v_lshl_add_u64 v[254:255], v[90:91], 0, s[16:17]
	s_mov_b32 m0, s94
	s_nop 0
	global_load_lds_dwordx4 v[254:255], off
	v_mfma_f32_32x32x16_bf16 v[18:33], v[110:113], v[102:105], v[18:33]
	v_mfma_f32_32x32x16_bf16 v[50:65], v[106:109], v[114:117], v[50:65]
	v_mfma_f32_32x32x16_bf16 v[2:17], v[110:113], v[114:117], v[2:17]
	s_mov_b32 m0, s1
	s_waitcnt vmcnt(0) lgkmcnt(0)
	s_barrier
; DI void gemm_out(const Params& p, char* lds) {
;     ...
;         for (int kt = 0; kt < 16; ++kt) {
;             if (kt + 1 < 16) OSTAGE((kt + 1) & 1, kt + 1);
;             const char* sb = lds + (kt & 1) * 28672; const char* sa = sb + 16384;
; #pragma unroll
;             for (int ks = 0; ks < 2; ++ks) {
;                 bf16x8 fw[4], fx[3];
; #pragma unroll
;                 for (int ct = 0; ct < 4; ++ct) fw[ct] = *(const bf16x8*)(sb + swz(wn * 64 + ct * 16 + q, 4 * ks + g));
; #pragma unroll
;                 for (int tt = 0; tt < 3; ++tt) fx[tt] = *(const bf16x8*)(sa + swz(wm * 48 + tt * 16 + q, 4 * ks + g));
; #pragma unroll
;                 for (int ct = 0; ct < 4; ++ct)
; #pragma unroll
;                     for (int tt = 0; tt < 3; ++tt) acc[ct][tt] = __builtin_amdgcn_mfma_f32_16x16x32_bf16(fw[ct], fx[tt], acc[ct][tt], 0, 0, 0);
;             }
;             __syncthreads();
;         }
	ds_read_b128 v[102:105], v74 offset:49152
	ds_read_b128 v[106:109], v96 offset:32768
	ds_read_b128 v[110:113], v96 offset:36864
	ds_read_b128 v[114:117], v74 offset:53248
	v_mfma_f32_32x32x16_bf16 v[34:49], v[242:245], v[238:241], v[34:49]
	v_mfma_f32_32x32x16_bf16 v[18:33], v[246:249], v[238:241], v[18:33]
	v_lshl_add_u64 v[254:255], v[76:77], 0, s[18:19]
	global_load_lds_dwordx4 v[254:255], off
	v_lshl_add_u64 v[254:255], v[78:79], 0, s[18:19]
	s_mov_b32 m0, s7
	s_nop 0
	global_load_lds_dwordx4 v[254:255], off
	v_mfma_f32_32x32x16_bf16 v[50:65], v[242:245], v[250:253], v[50:65]
	v_lshl_add_u64 v[254:255], v[80:81], 0, s[18:19]
	s_mov_b32 m0, s38
	s_nop 0
	global_load_lds_dwordx4 v[254:255], off
	v_mfma_f32_32x32x16_bf16 v[2:17], v[246:249], v[250:253], v[2:17]
	s_waitcnt lgkmcnt(0)
	ds_read_b128 v[238:241], v95 offset:49152
	ds_read_b128 v[242:245], v97 offset:32768
	ds_read_b128 v[246:249], v97 offset:36864
	ds_read_b128 v[250:253], v95 offset:53248
	v_mfma_f32_32x32x16_bf16 v[34:49], v[106:109], v[102:105], v[34:49]
	v_lshl_add_u64 v[254:255], v[82:83], 0, s[18:19]
	s_mov_b32 m0, s39
	s_nop 0
	global_load_lds_dwordx4 v[254:255], off
	v_mfma_f32_32x32x16_bf16 v[18:33], v[110:113], v[102:105], v[18:33]
	v_lshl_add_u64 v[254:255], v[84:85], 0, s[18:19]
	s_mov_b32 m0, s50
	s_nop 0
	global_load_lds_dwordx4 v[254:255], off
	v_mfma_f32_32x32x16_bf16 v[50:65], v[106:109], v[114:117], v[50:65]
	v_mfma_f32_32x32x16_bf16 v[2:17], v[110:113], v[114:117], v[2:17]
	s_waitcnt lgkmcnt(0)
	ds_read_b128 v[102:105], v98 offset:49152
	ds_read_b128 v[106:109], v99 offset:32768
	ds_read_b128 v[110:113], v99 offset:36864
	ds_read_b128 v[114:117], v98 offset:53248
	v_mfma_f32_32x32x16_bf16 v[34:49], v[242:245], v[238:241], v[34:49]
	v_lshl_add_u64 v[254:255], v[86:87], 0, s[18:19]
	s_mov_b32 m0, s51
	s_nop 0
	global_load_lds_dwordx4 v[254:255], off
	v_mfma_f32_32x32x16_bf16 v[18:33], v[246:249], v[238:241], v[18:33]
	v_lshl_add_u64 v[254:255], v[88:89], 0, s[18:19]
	s_mov_b32 m0, s83
	s_nop 0
	global_load_lds_dwordx4 v[254:255], off
	v_mfma_f32_32x32x16_bf16 v[50:65], v[242:245], v[250:253], v[50:65]
	v_mfma_f32_32x32x16_bf16 v[2:17], v[246:249], v[250:253], v[2:17]
	s_waitcnt lgkmcnt(0)
	ds_read_b128 v[238:241], v100 offset:49152
	ds_read_b128 v[242:245], v101 offset:32768
	ds_read_b128 v[246:249], v101 offset:36864
	ds_read_b128 v[250:253], v100 offset:53248
	v_mfma_f32_32x32x16_bf16 v[34:49], v[106:109], v[102:105], v[34:49]
	v_lshl_add_u64 v[254:255], v[90:91], 0, s[18:19]
	s_mov_b32 m0, s90
	s_nop 0
	global_load_lds_dwordx4 v[254:255], off
	v_mfma_f32_32x32x16_bf16 v[18:33], v[110:113], v[102:105], v[18:33]
	v_mfma_f32_32x32x16_bf16 v[50:65], v[106:109], v[114:117], v[50:65]
	v_mfma_f32_32x32x16_bf16 v[2:17], v[110:113], v[114:117], v[2:17]
	s_mov_b32 m0, s86
	s_waitcnt vmcnt(0) lgkmcnt(0)
	s_barrier
	ds_read_b128 v[102:105], v74 offset:16384
	ds_read_b128 v[106:109], v96
	ds_read_b128 v[110:113], v96 offset:4096
	ds_read_b128 v[114:117], v74 offset:20480
	v_mfma_f32_32x32x16_bf16 v[34:49], v[242:245], v[238:241], v[34:49]
	v_mfma_f32_32x32x16_bf16 v[18:33], v[246:249], v[238:241], v[18:33]
	v_lshl_add_u64 v[254:255], v[76:77], 0, s[20:21]
	global_load_lds_dwordx4 v[254:255], off
	v_lshl_add_u64 v[254:255], v[78:79], 0, s[20:21]
	s_mov_b32 m0, s87
	s_nop 0
	global_load_lds_dwordx4 v[254:255], off
	v_mfma_f32_32x32x16_bf16 v[50:65], v[242:245], v[250:253], v[50:65]
	v_lshl_add_u64 v[254:255], v[80:81], 0, s[20:21]
	s_mov_b32 m0, s88
	s_nop 0
	global_load_lds_dwordx4 v[254:255], off
	v_mfma_f32_32x32x16_bf16 v[2:17], v[246:249], v[250:253], v[2:17]
	s_waitcnt lgkmcnt(0)
	ds_read_b128 v[238:241], v95 offset:16384
	ds_read_b128 v[242:245], v97
	ds_read_b128 v[246:249], v97 offset:4096
	ds_read_b128 v[250:253], v95 offset:20480
	v_mfma_f32_32x32x16_bf16 v[34:49], v[106:109], v[102:105], v[34:49]
	v_lshl_add_u64 v[254:255], v[82:83], 0, s[20:21]
	s_mov_b32 m0, s89
	s_nop 0
	global_load_lds_dwordx4 v[254:255], off
	v_mfma_f32_32x32x16_bf16 v[18:33], v[110:113], v[102:105], v[18:33]
	v_lshl_add_u64 v[254:255], v[84:85], 0, s[20:21]
	s_mov_b32 m0, s91
	s_nop 0
	global_load_lds_dwordx4 v[254:255], off
	v_mfma_f32_32x32x16_bf16 v[50:65], v[106:109], v[114:117], v[50:65]
	v_mfma_f32_32x32x16_bf16 v[2:17], v[110:113], v[114:117], v[2:17]
	s_waitcnt lgkmcnt(0)
	ds_read_b128 v[102:105], v98 offset:16384
	ds_read_b128 v[106:109], v99
	ds_read_b128 v[110:113], v99 offset:4096
	ds_read_b128 v[114:117], v98 offset:20480
	v_mfma_f32_32x32x16_bf16 v[34:49], v[242:245], v[238:241], v[34:49]
	v_lshl_add_u64 v[254:255], v[86:87], 0, s[20:21]
	s_mov_b32 m0, s92
	s_nop 0
	global_load_lds_dwordx4 v[254:255], off
	v_mfma_f32_32x32x16_bf16 v[18:33], v[246:249], v[238:241], v[18:33]
	v_lshl_add_u64 v[254:255], v[88:89], 0, s[20:21]
	s_mov_b32 m0, s93
	s_nop 0
	global_load_lds_dwordx4 v[254:255], off
	v_mfma_f32_32x32x16_bf16 v[50:65], v[242:245], v[250:253], v[50:65]
	v_mfma_f32_32x32x16_bf16 v[2:17], v[246:249], v[250:253], v[2:17]
	s_waitcnt lgkmcnt(0)
	ds_read_b128 v[238:241], v100 offset:16384
	ds_read_b128 v[242:245], v101
	ds_read_b128 v[246:249], v101 offset:4096
	ds_read_b128 v[250:253], v100 offset:20480
	v_mfma_f32_32x32x16_bf16 v[34:49], v[106:109], v[102:105], v[34:49]
	v_lshl_add_u64 v[254:255], v[90:91], 0, s[20:21]
	s_mov_b32 m0, s94
	s_nop 0
	global_load_lds_dwordx4 v[254:255], off
	v_mfma_f32_32x32x16_bf16 v[18:33], v[110:113], v[102:105], v[18:33]
	v_mfma_f32_32x32x16_bf16 v[50:65], v[106:109], v[114:117], v[50:65]
	v_mfma_f32_32x32x16_bf16 v[2:17], v[110:113], v[114:117], v[2:17]
	s_mov_b32 m0, s1
	s_waitcnt vmcnt(0) lgkmcnt(0)
	s_barrier
; DI void gemm_out(const Params& p, char* lds) {
;     ...
;         for (int kt = 0; kt < 16; ++kt) {
;             if (kt + 1 < 16) OSTAGE((kt + 1) & 1, kt + 1);
;             const char* sb = lds + (kt & 1) * 28672; const char* sa = sb + 16384;
; #pragma unroll
;             for (int ks = 0; ks < 2; ++ks) {
;                 bf16x8 fw[4], fx[3];
; #pragma unroll
;                 for (int ct = 0; ct < 4; ++ct) fw[ct] = *(const bf16x8*)(sb + swz(wn * 64 + ct * 16 + q, 4 * ks + g));
; #pragma unroll
;                 for (int tt = 0; tt < 3; ++tt) fx[tt] = *(const bf16x8*)(sa + swz(wm * 48 + tt * 16 + q, 4 * ks + g));
; #pragma unroll
;                 for (int ct = 0; ct < 4; ++ct)
; #pragma unroll
;                     for (int tt = 0; tt < 3; ++tt) acc[ct][tt] = __builtin_amdgcn_mfma_f32_16x16x32_bf16(fw[ct], fx[tt], acc[ct][tt], 0, 0, 0);
;             }
;             __syncthreads();
;         }
	ds_read_b128 v[102:105], v74 offset:49152
	ds_read_b128 v[106:109], v96 offset:32768
	ds_read_b128 v[110:113], v96 offset:36864
	ds_read_b128 v[114:117], v74 offset:53248
	v_mfma_f32_32x32x16_bf16 v[34:49], v[242:245], v[238:241], v[34:49]
	v_mfma_f32_32x32x16_bf16 v[18:33], v[246:249], v[238:241], v[18:33]
	v_lshl_add_u64 v[254:255], v[76:77], 0, s[22:23]
	global_load_lds_dwordx4 v[254:255], off
	v_lshl_add_u64 v[254:255], v[78:79], 0, s[22:23]
	s_mov_b32 m0, s7
	s_nop 0
	global_load_lds_dwordx4 v[254:255], off
	v_mfma_f32_32x32x16_bf16 v[50:65], v[242:245], v[250:253], v[50:65]
	v_lshl_add_u64 v[254:255], v[80:81], 0, s[22:23]
	s_mov_b32 m0, s38
	s_nop 0
	global_load_lds_dwordx4 v[254:255], off
	v_mfma_f32_32x32x16_bf16 v[2:17], v[246:249], v[250:253], v[2:17]
	s_waitcnt lgkmcnt(0)
	ds_read_b128 v[238:241], v95 offset:49152
	ds_read_b128 v[242:245], v97 offset:32768
	ds_read_b128 v[246:249], v97 offset:36864
	ds_read_b128 v[250:253], v95 offset:53248
	v_mfma_f32_32x32x16_bf16 v[34:49], v[106:109], v[102:105], v[34:49]
	v_lshl_add_u64 v[254:255], v[82:83], 0, s[22:23]
	s_mov_b32 m0, s39
	s_nop 0
	global_load_lds_dwordx4 v[254:255], off
	v_mfma_f32_32x32x16_bf16 v[18:33], v[110:113], v[102:105], v[18:33]
	v_lshl_add_u64 v[254:255], v[84:85], 0, s[22:23]
	s_mov_b32 m0, s50
	s_nop 0
	global_load_lds_dwordx4 v[254:255], off
	v_mfma_f32_32x32x16_bf16 v[50:65], v[106:109], v[114:117], v[50:65]
	v_mfma_f32_32x32x16_bf16 v[2:17], v[110:113], v[114:117], v[2:17]
	s_waitcnt lgkmcnt(0)
	ds_read_b128 v[102:105], v98 offset:49152
	ds_read_b128 v[106:109], v99 offset:32768
	ds_read_b128 v[110:113], v99 offset:36864
	ds_read_b128 v[114:117], v98 offset:53248
	v_mfma_f32_32x32x16_bf16 v[34:49], v[242:245], v[238:241], v[34:49]
	v_lshl_add_u64 v[254:255], v[86:87], 0, s[22:23]
	s_mov_b32 m0, s51
	s_nop 0
	global_load_lds_dwordx4 v[254:255], off
	v_mfma_f32_32x32x16_bf16 v[18:33], v[246:249], v[238:241], v[18:33]
	v_lshl_add_u64 v[254:255], v[88:89], 0, s[22:23]
	s_mov_b32 m0, s83
	s_nop 0
	global_load_lds_dwordx4 v[254:255], off
	v_mfma_f32_32x32x16_bf16 v[50:65], v[242:245], v[250:253], v[50:65]
	v_mfma_f32_32x32x16_bf16 v[2:17], v[246:249], v[250:253], v[2:17]
	s_waitcnt lgkmcnt(0)
	ds_read_b128 v[238:241], v100 offset:49152
	ds_read_b128 v[242:245], v101 offset:32768
	ds_read_b128 v[246:249], v101 offset:36864
	ds_read_b128 v[250:253], v100 offset:53248
	v_mfma_f32_32x32x16_bf16 v[34:49], v[106:109], v[102:105], v[34:49]
	v_lshl_add_u64 v[254:255], v[90:91], 0, s[22:23]
	s_mov_b32 m0, s90
	s_nop 0
	global_load_lds_dwordx4 v[254:255], off
	v_mfma_f32_32x32x16_bf16 v[18:33], v[110:113], v[102:105], v[18:33]
	v_mfma_f32_32x32x16_bf16 v[50:65], v[106:109], v[114:117], v[50:65]
	v_mfma_f32_32x32x16_bf16 v[2:17], v[110:113], v[114:117], v[2:17]
	s_mov_b32 m0, s86
	s_waitcnt vmcnt(0) lgkmcnt(0)
	s_barrier
	ds_read_b128 v[102:105], v74 offset:16384
	ds_read_b128 v[106:109], v96
	ds_read_b128 v[110:113], v96 offset:4096
	ds_read_b128 v[114:117], v74 offset:20480
	v_mfma_f32_32x32x16_bf16 v[34:49], v[242:245], v[238:241], v[34:49]
	v_mfma_f32_32x32x16_bf16 v[18:33], v[246:249], v[238:241], v[18:33]
	v_lshl_add_u64 v[254:255], v[76:77], 0, s[24:25]
	global_load_lds_dwordx4 v[254:255], off
	v_lshl_add_u64 v[254:255], v[78:79], 0, s[24:25]
	s_mov_b32 m0, s87
	s_nop 0
	global_load_lds_dwordx4 v[254:255], off
	v_mfma_f32_32x32x16_bf16 v[50:65], v[242:245], v[250:253], v[50:65]
	v_lshl_add_u64 v[254:255], v[80:81], 0, s[24:25]
	s_mov_b32 m0, s88
	s_nop 0
	global_load_lds_dwordx4 v[254:255], off
	v_mfma_f32_32x32x16_bf16 v[2:17], v[246:249], v[250:253], v[2:17]
	s_waitcnt lgkmcnt(0)
	ds_read_b128 v[238:241], v95 offset:16384
	ds_read_b128 v[242:245], v97
	ds_read_b128 v[246:249], v97 offset:4096
	ds_read_b128 v[250:253], v95 offset:20480
	v_mfma_f32_32x32x16_bf16 v[34:49], v[106:109], v[102:105], v[34:49]
	v_lshl_add_u64 v[254:255], v[82:83], 0, s[24:25]
	s_mov_b32 m0, s89
	s_nop 0
	global_load_lds_dwordx4 v[254:255], off
	v_mfma_f32_32x32x16_bf16 v[18:33], v[110:113], v[102:105], v[18:33]
	v_lshl_add_u64 v[254:255], v[84:85], 0, s[24:25]
	s_mov_b32 m0, s91
	s_nop 0
	global_load_lds_dwordx4 v[254:255], off
	v_mfma_f32_32x32x16_bf16 v[50:65], v[106:109], v[114:117], v[50:65]
	v_mfma_f32_32x32x16_bf16 v[2:17], v[110:113], v[114:117], v[2:17]
	s_waitcnt lgkmcnt(0)
	ds_read_b128 v[102:105], v98 offset:16384
	ds_read_b128 v[106:109], v99
	ds_read_b128 v[110:113], v99 offset:4096
	ds_read_b128 v[114:117], v98 offset:20480
	v_mfma_f32_32x32x16_bf16 v[34:49], v[242:245], v[238:241], v[34:49]
	v_lshl_add_u64 v[254:255], v[86:87], 0, s[24:25]
	s_mov_b32 m0, s92
	s_nop 0
	global_load_lds_dwordx4 v[254:255], off
	v_mfma_f32_32x32x16_bf16 v[18:33], v[246:249], v[238:241], v[18:33]
	v_lshl_add_u64 v[254:255], v[88:89], 0, s[24:25]
	s_mov_b32 m0, s93
	s_nop 0
	global_load_lds_dwordx4 v[254:255], off
	v_mfma_f32_32x32x16_bf16 v[50:65], v[242:245], v[250:253], v[50:65]
	v_mfma_f32_32x32x16_bf16 v[2:17], v[246:249], v[250:253], v[2:17]
	s_waitcnt lgkmcnt(0)
	ds_read_b128 v[238:241], v100 offset:16384
	ds_read_b128 v[242:245], v101
	ds_read_b128 v[246:249], v101 offset:4096
	ds_read_b128 v[250:253], v100 offset:20480
	v_mfma_f32_32x32x16_bf16 v[34:49], v[106:109], v[102:105], v[34:49]
	v_lshl_add_u64 v[254:255], v[90:91], 0, s[24:25]
	s_mov_b32 m0, s94
	s_nop 0
	global_load_lds_dwordx4 v[254:255], off
	v_mfma_f32_32x32x16_bf16 v[18:33], v[110:113], v[102:105], v[18:33]
	v_mfma_f32_32x32x16_bf16 v[50:65], v[106:109], v[114:117], v[50:65]
	v_mfma_f32_32x32x16_bf16 v[2:17], v[110:113], v[114:117], v[2:17]
	s_mov_b32 m0, s1
	s_waitcnt vmcnt(0) lgkmcnt(0)
	s_barrier
; DI void gemm_out(const Params& p, char* lds) {
;     ...
;         for (int kt = 0; kt < 16; ++kt) {
;             if (kt + 1 < 16) OSTAGE((kt + 1) & 1, kt + 1);
;             const char* sb = lds + (kt & 1) * 28672; const char* sa = sb + 16384;
; #pragma unroll
;             for (int ks = 0; ks < 2; ++ks) {
;                 bf16x8 fw[4], fx[3];
; #pragma unroll
;                 for (int ct = 0; ct < 4; ++ct) fw[ct] = *(const bf16x8*)(sb + swz(wn * 64 + ct * 16 + q, 4 * ks + g));
; #pragma unroll
;                 for (int tt = 0; tt < 3; ++tt) fx[tt] = *(const bf16x8*)(sa + swz(wm * 48 + tt * 16 + q, 4 * ks + g));
; #pragma unroll
;                 for (int ct = 0; ct < 4; ++ct)
; #pragma unroll
;                     for (int tt = 0; tt < 3; ++tt) acc[ct][tt] = __builtin_amdgcn_mfma_f32_16x16x32_bf16(fw[ct], fx[tt], acc[ct][tt], 0, 0, 0);
;             }
;             __syncthreads();
;         }
	ds_read_b128 v[102:105], v74 offset:49152
	ds_read_b128 v[106:109], v96 offset:32768
	ds_read_b128 v[110:113], v96 offset:36864
	ds_read_b128 v[114:117], v74 offset:53248
	v_mfma_f32_32x32x16_bf16 v[34:49], v[242:245], v[238:241], v[34:49]
	v_mfma_f32_32x32x16_bf16 v[18:33], v[246:249], v[238:241], v[18:33]
	v_lshl_add_u64 v[254:255], v[76:77], 0, s[26:27]
	global_load_lds_dwordx4 v[254:255], off
	v_lshl_add_u64 v[254:255], v[78:79], 0, s[26:27]
	s_mov_b32 m0, s7
	s_nop 0
	global_load_lds_dwordx4 v[254:255], off
	v_mfma_f32_32x32x16_bf16 v[50:65], v[242:245], v[250:253], v[50:65]
	v_lshl_add_u64 v[254:255], v[80:81], 0, s[26:27]
	s_mov_b32 m0, s38
	s_nop 0
	global_load_lds_dwordx4 v[254:255], off
	v_mfma_f32_32x32x16_bf16 v[2:17], v[246:249], v[250:253], v[2:17]
	s_waitcnt lgkmcnt(0)
	ds_read_b128 v[238:241], v95 offset:49152
	ds_read_b128 v[242:245], v97 offset:32768
	ds_read_b128 v[246:249], v97 offset:36864
	ds_read_b128 v[250:253], v95 offset:53248
	v_mfma_f32_32x32x16_bf16 v[34:49], v[106:109], v[102:105], v[34:49]
	v_lshl_add_u64 v[254:255], v[82:83], 0, s[26:27]
	s_mov_b32 m0, s39
	s_nop 0
	global_load_lds_dwordx4 v[254:255], off
	v_mfma_f32_32x32x16_bf16 v[18:33], v[110:113], v[102:105], v[18:33]
	v_lshl_add_u64 v[254:255], v[84:85], 0, s[26:27]
	s_mov_b32 m0, s50
	s_nop 0
	global_load_lds_dwordx4 v[254:255], off
	v_mfma_f32_32x32x16_bf16 v[50:65], v[106:109], v[114:117], v[50:65]
	v_mfma_f32_32x32x16_bf16 v[2:17], v[110:113], v[114:117], v[2:17]
	s_waitcnt lgkmcnt(0)
	ds_read_b128 v[102:105], v98 offset:49152
	ds_read_b128 v[106:109], v99 offset:32768
	ds_read_b128 v[110:113], v99 offset:36864
	ds_read_b128 v[114:117], v98 offset:53248
	v_mfma_f32_32x32x16_bf16 v[34:49], v[242:245], v[238:241], v[34:49]
	v_lshl_add_u64 v[254:255], v[86:87], 0, s[26:27]
	s_mov_b32 m0, s51
	s_nop 0
	global_load_lds_dwordx4 v[254:255], off
	v_mfma_f32_32x32x16_bf16 v[18:33], v[246:249], v[238:241], v[18:33]
	v_lshl_add_u64 v[254:255], v[88:89], 0, s[26:27]
	s_mov_b32 m0, s83
	s_nop 0
	global_load_lds_dwordx4 v[254:255], off
	v_mfma_f32_32x32x16_bf16 v[50:65], v[242:245], v[250:253], v[50:65]
	v_mfma_f32_32x32x16_bf16 v[2:17], v[246:249], v[250:253], v[2:17]
	s_waitcnt lgkmcnt(0)
	ds_read_b128 v[238:241], v100 offset:49152
	ds_read_b128 v[242:245], v101 offset:32768
	ds_read_b128 v[246:249], v101 offset:36864
	ds_read_b128 v[250:253], v100 offset:53248
	v_mfma_f32_32x32x16_bf16 v[34:49], v[106:109], v[102:105], v[34:49]
	v_lshl_add_u64 v[254:255], v[90:91], 0, s[26:27]
	s_mov_b32 m0, s90
	s_nop 0
	global_load_lds_dwordx4 v[254:255], off
	v_mfma_f32_32x32x16_bf16 v[18:33], v[110:113], v[102:105], v[18:33]
	v_mfma_f32_32x32x16_bf16 v[50:65], v[106:109], v[114:117], v[50:65]
	v_mfma_f32_32x32x16_bf16 v[2:17], v[110:113], v[114:117], v[2:17]
	s_mov_b32 m0, s86
	s_waitcnt vmcnt(0) lgkmcnt(0)
	s_barrier
	ds_read_b128 v[102:105], v74 offset:16384
	ds_read_b128 v[106:109], v96
	ds_read_b128 v[110:113], v96 offset:4096
	ds_read_b128 v[114:117], v74 offset:20480
	v_mfma_f32_32x32x16_bf16 v[34:49], v[242:245], v[238:241], v[34:49]
	v_mfma_f32_32x32x16_bf16 v[18:33], v[246:249], v[238:241], v[18:33]
	v_lshl_add_u64 v[254:255], v[76:77], 0, s[28:29]
	global_load_lds_dwordx4 v[254:255], off
	v_lshl_add_u64 v[254:255], v[78:79], 0, s[28:29]
	s_mov_b32 m0, s87
	s_nop 0
	global_load_lds_dwordx4 v[254:255], off
	v_mfma_f32_32x32x16_bf16 v[50:65], v[242:245], v[250:253], v[50:65]
	v_lshl_add_u64 v[254:255], v[80:81], 0, s[28:29]
	s_mov_b32 m0, s88
	s_nop 0
	global_load_lds_dwordx4 v[254:255], off
	v_mfma_f32_32x32x16_bf16 v[2:17], v[246:249], v[250:253], v[2:17]
	s_waitcnt lgkmcnt(0)
	ds_read_b128 v[238:241], v95 offset:16384
	ds_read_b128 v[242:245], v97
	ds_read_b128 v[246:249], v97 offset:4096
	ds_read_b128 v[250:253], v95 offset:20480
	v_mfma_f32_32x32x16_bf16 v[34:49], v[106:109], v[102:105], v[34:49]
	v_lshl_add_u64 v[254:255], v[82:83], 0, s[28:29]
	s_mov_b32 m0, s89
	s_nop 0
	global_load_lds_dwordx4 v[254:255], off
	v_mfma_f32_32x32x16_bf16 v[18:33], v[110:113], v[102:105], v[18:33]
	v_lshl_add_u64 v[254:255], v[84:85], 0, s[28:29]
	s_mov_b32 m0, s91
	s_nop 0
	global_load_lds_dwordx4 v[254:255], off
	v_mfma_f32_32x32x16_bf16 v[50:65], v[106:109], v[114:117], v[50:65]
	v_mfma_f32_32x32x16_bf16 v[2:17], v[110:113], v[114:117], v[2:17]
	s_waitcnt lgkmcnt(0)
	ds_read_b128 v[102:105], v98 offset:16384
	ds_read_b128 v[106:109], v99
	ds_read_b128 v[110:113], v99 offset:4096
	ds_read_b128 v[114:117], v98 offset:20480
	v_mfma_f32_32x32x16_bf16 v[34:49], v[242:245], v[238:241], v[34:49]
	v_lshl_add_u64 v[254:255], v[86:87], 0, s[28:29]
	s_mov_b32 m0, s92
	s_nop 0
	global_load_lds_dwordx4 v[254:255], off
	v_mfma_f32_32x32x16_bf16 v[18:33], v[246:249], v[238:241], v[18:33]
	v_lshl_add_u64 v[254:255], v[88:89], 0, s[28:29]
	s_mov_b32 m0, s93
	s_nop 0
	global_load_lds_dwordx4 v[254:255], off
	v_mfma_f32_32x32x16_bf16 v[50:65], v[242:245], v[250:253], v[50:65]
	v_mfma_f32_32x32x16_bf16 v[2:17], v[246:249], v[250:253], v[2:17]
	s_waitcnt lgkmcnt(0)
	ds_read_b128 v[238:241], v100 offset:16384
	ds_read_b128 v[242:245], v101
	ds_read_b128 v[246:249], v101 offset:4096
	ds_read_b128 v[250:253], v100 offset:20480
	v_mfma_f32_32x32x16_bf16 v[34:49], v[106:109], v[102:105], v[34:49]
	v_lshl_add_u64 v[254:255], v[90:91], 0, s[28:29]
	s_mov_b32 m0, s94
	s_nop 0
	global_load_lds_dwordx4 v[254:255], off
	v_mfma_f32_32x32x16_bf16 v[18:33], v[110:113], v[102:105], v[18:33]
	v_mfma_f32_32x32x16_bf16 v[50:65], v[106:109], v[114:117], v[50:65]
	v_mfma_f32_32x32x16_bf16 v[2:17], v[110:113], v[114:117], v[2:17]
	s_mov_b32 m0, s1
	s_waitcnt vmcnt(0) lgkmcnt(0)
	s_barrier
; DI void gemm_out(const Params& p, char* lds) {
;     ...
;         for (int kt = 0; kt < 16; ++kt) {
;             if (kt + 1 < 16) OSTAGE((kt + 1) & 1, kt + 1);
;             const char* sb = lds + (kt & 1) * 28672; const char* sa = sb + 16384;
; #pragma unroll
;             for (int ks = 0; ks < 2; ++ks) {
;                 bf16x8 fw[4], fx[3];
; #pragma unroll
;                 for (int ct = 0; ct < 4; ++ct) fw[ct] = *(const bf16x8*)(sb + swz(wn * 64 + ct * 16 + q, 4 * ks + g));
; #pragma unroll
;                 for (int tt = 0; tt < 3; ++tt) fx[tt] = *(const bf16x8*)(sa + swz(wm * 48 + tt * 16 + q, 4 * ks + g));
; #pragma unroll
;                 for (int ct = 0; ct < 4; ++ct)
; #pragma unroll
;                     for (int tt = 0; tt < 3; ++tt) acc[ct][tt] = __builtin_amdgcn_mfma_f32_16x16x32_bf16(fw[ct], fx[tt], acc[ct][tt], 0, 0, 0);
;             }
;             __syncthreads();
;         }
	ds_read_b128 v[102:105], v74 offset:49152
	ds_read_b128 v[106:109], v96 offset:32768
	ds_read_b128 v[110:113], v96 offset:36864
	ds_read_b128 v[114:117], v74 offset:53248
	v_mfma_f32_32x32x16_bf16 v[34:49], v[242:245], v[238:241], v[34:49]
	v_mfma_f32_32x32x16_bf16 v[18:33], v[246:249], v[238:241], v[18:33]
	v_lshl_add_u64 v[254:255], v[76:77], 0, s[30:31]
	global_load_lds_dwordx4 v[254:255], off
	v_lshl_add_u64 v[254:255], v[78:79], 0, s[30:31]
	s_mov_b32 m0, s7
	s_nop 0
	global_load_lds_dwordx4 v[254:255], off
	v_mfma_f32_32x32x16_bf16 v[50:65], v[242:245], v[250:253], v[50:65]
	v_lshl_add_u64 v[254:255], v[80:81], 0, s[30:31]
	s_mov_b32 m0, s38
	s_nop 0
	global_load_lds_dwordx4 v[254:255], off
	v_mfma_f32_32x32x16_bf16 v[2:17], v[246:249], v[250:253], v[2:17]
	s_waitcnt lgkmcnt(0)
	ds_read_b128 v[238:241], v95 offset:49152
	ds_read_b128 v[242:245], v97 offset:32768
	ds_read_b128 v[246:249], v97 offset:36864
	ds_read_b128 v[250:253], v95 offset:53248
	v_mfma_f32_32x32x16_bf16 v[34:49], v[106:109], v[102:105], v[34:49]
	v_lshl_add_u64 v[254:255], v[82:83], 0, s[30:31]
	s_mov_b32 m0, s39
	s_nop 0
	global_load_lds_dwordx4 v[254:255], off
	v_mfma_f32_32x32x16_bf16 v[18:33], v[110:113], v[102:105], v[18:33]
	v_lshl_add_u64 v[254:255], v[84:85], 0, s[30:31]
	s_mov_b32 m0, s50
	s_nop 0
	global_load_lds_dwordx4 v[254:255], off
	v_mfma_f32_32x32x16_bf16 v[50:65], v[106:109], v[114:117], v[50:65]
	v_mfma_f32_32x32x16_bf16 v[2:17], v[110:113], v[114:117], v[2:17]
	s_waitcnt lgkmcnt(0)
	ds_read_b128 v[102:105], v98 offset:49152
	ds_read_b128 v[106:109], v99 offset:32768
	ds_read_b128 v[110:113], v99 offset:36864
	ds_read_b128 v[114:117], v98 offset:53248
	v_mfma_f32_32x32x16_bf16 v[34:49], v[242:245], v[238:241], v[34:49]
	v_lshl_add_u64 v[254:255], v[86:87], 0, s[30:31]
	s_mov_b32 m0, s51
	s_nop 0
	global_load_lds_dwordx4 v[254:255], off
	v_mfma_f32_32x32x16_bf16 v[18:33], v[246:249], v[238:241], v[18:33]
	v_lshl_add_u64 v[254:255], v[88:89], 0, s[30:31]
	s_mov_b32 m0, s83
	s_nop 0
	global_load_lds_dwordx4 v[254:255], off
	v_mfma_f32_32x32x16_bf16 v[50:65], v[242:245], v[250:253], v[50:65]
	v_mfma_f32_32x32x16_bf16 v[2:17], v[246:249], v[250:253], v[2:17]
	s_waitcnt lgkmcnt(0)
	ds_read_b128 v[238:241], v100 offset:49152
	ds_read_b128 v[242:245], v101 offset:32768
	ds_read_b128 v[246:249], v101 offset:36864
	ds_read_b128 v[250:253], v100 offset:53248
	v_mfma_f32_32x32x16_bf16 v[34:49], v[106:109], v[102:105], v[34:49]
	v_lshl_add_u64 v[254:255], v[90:91], 0, s[30:31]
	s_mov_b32 m0, s90
	s_nop 0
	global_load_lds_dwordx4 v[254:255], off
	v_mfma_f32_32x32x16_bf16 v[18:33], v[110:113], v[102:105], v[18:33]
	v_mfma_f32_32x32x16_bf16 v[50:65], v[106:109], v[114:117], v[50:65]
	v_mfma_f32_32x32x16_bf16 v[2:17], v[110:113], v[114:117], v[2:17]
	s_mov_b32 m0, s86
	s_waitcnt vmcnt(0) lgkmcnt(0)
	s_barrier
	ds_read_b128 v[102:105], v74 offset:16384
	ds_read_b128 v[106:109], v96
	ds_read_b128 v[110:113], v96 offset:4096
	ds_read_b128 v[114:117], v74 offset:20480
	v_mfma_f32_32x32x16_bf16 v[34:49], v[242:245], v[238:241], v[34:49]
	v_mfma_f32_32x32x16_bf16 v[18:33], v[246:249], v[238:241], v[18:33]
	v_lshl_add_u64 v[254:255], v[76:77], 0, s[36:37]
	global_load_lds_dwordx4 v[254:255], off
	v_lshl_add_u64 v[254:255], v[78:79], 0, s[36:37]
	s_mov_b32 m0, s87
	s_nop 0
	global_load_lds_dwordx4 v[254:255], off
	v_mfma_f32_32x32x16_bf16 v[50:65], v[242:245], v[250:253], v[50:65]
	v_lshl_add_u64 v[254:255], v[80:81], 0, s[36:37]
	s_mov_b32 m0, s88
	s_nop 0
	global_load_lds_dwordx4 v[254:255], off
	v_mfma_f32_32x32x16_bf16 v[2:17], v[246:249], v[250:253], v[2:17]
	s_waitcnt lgkmcnt(0)
	ds_read_b128 v[238:241], v95 offset:16384
	ds_read_b128 v[242:245], v97
	ds_read_b128 v[246:249], v97 offset:4096
	ds_read_b128 v[250:253], v95 offset:20480
	v_mfma_f32_32x32x16_bf16 v[34:49], v[106:109], v[102:105], v[34:49]
	v_lshl_add_u64 v[254:255], v[82:83], 0, s[36:37]
	s_mov_b32 m0, s89
	s_nop 0
	global_load_lds_dwordx4 v[254:255], off
	v_mfma_f32_32x32x16_bf16 v[18:33], v[110:113], v[102:105], v[18:33]
	v_lshl_add_u64 v[254:255], v[84:85], 0, s[36:37]
	s_mov_b32 m0, s91
	s_nop 0
	global_load_lds_dwordx4 v[254:255], off
	v_mfma_f32_32x32x16_bf16 v[50:65], v[106:109], v[114:117], v[50:65]
	v_mfma_f32_32x32x16_bf16 v[2:17], v[110:113], v[114:117], v[2:17]
	s_waitcnt lgkmcnt(0)
	ds_read_b128 v[102:105], v98 offset:16384
	ds_read_b128 v[106:109], v99
	ds_read_b128 v[110:113], v99 offset:4096
	ds_read_b128 v[114:117], v98 offset:20480
	v_mfma_f32_32x32x16_bf16 v[34:49], v[242:245], v[238:241], v[34:49]
	v_lshl_add_u64 v[254:255], v[86:87], 0, s[36:37]
	s_mov_b32 m0, s92
	s_nop 0
	global_load_lds_dwordx4 v[254:255], off
	v_mfma_f32_32x32x16_bf16 v[18:33], v[246:249], v[238:241], v[18:33]
	v_lshl_add_u64 v[254:255], v[88:89], 0, s[36:37]
	s_mov_b32 m0, s93
	s_nop 0
	global_load_lds_dwordx4 v[254:255], off
	v_mfma_f32_32x32x16_bf16 v[50:65], v[242:245], v[250:253], v[50:65]
	v_mfma_f32_32x32x16_bf16 v[2:17], v[246:249], v[250:253], v[2:17]
	s_waitcnt lgkmcnt(0)
	ds_read_b128 v[238:241], v100 offset:16384
	ds_read_b128 v[242:245], v101
	ds_read_b128 v[246:249], v101 offset:4096
	ds_read_b128 v[250:253], v100 offset:20480
	v_mfma_f32_32x32x16_bf16 v[34:49], v[106:109], v[102:105], v[34:49]
	v_lshl_add_u64 v[254:255], v[90:91], 0, s[36:37]
	s_mov_b32 m0, s94
	s_nop 0
	global_load_lds_dwordx4 v[254:255], off
	v_mfma_f32_32x32x16_bf16 v[18:33], v[110:113], v[102:105], v[18:33]
	v_mfma_f32_32x32x16_bf16 v[50:65], v[106:109], v[114:117], v[50:65]
	v_mfma_f32_32x32x16_bf16 v[2:17], v[110:113], v[114:117], v[2:17]
	s_mov_b32 m0, s1
	s_waitcnt vmcnt(0) lgkmcnt(0)
	s_barrier
; DI void gemm_out(const Params& p, char* lds) {
;     ...
;         const int mt = tile >> 3, nt = tile & 7; const int m0 = mt * 96, n0 = nt * 128;
;         f32x4 acc[4][3];
; #pragma unroll
;         for (int a = 0; a < 4; ++a)
; #pragma unroll
;             for (int b = 0; b < 3; ++b) acc[a][b] = (f32x4){0.f, 0.f, 0.f, 0.f};
;         unsigned soffb[4], soffa[3];
; #pragma unroll
;         for (int i = 0; i < 4; ++i) { const int row = 8 * (i * 4 + wave) + (lane >> 3); const int ch = (lane & 7) ^ ((row >> 1) & 7); soffb[i] = (unsigned)(row * 1024 + ch * 8); }
; #pragma unroll
;         for (int i = 0; i < 3; ++i) { const int row = 8 * (i * 4 + wave) + (lane >> 3); const int ch = (lane & 7) ^ ((row >> 1) & 7); soffa[i] = (unsigned)(row * 1024 + ch * 8); }
;         const u16* ga = A + (size_t)m0 * 1024; const u16* gb = B + (size_t)n0 * 1024;
;     ...
;         OSTAGE(0, 0);
;     ...
;         for (int kt = 0; kt < 16; ++kt) {
;             if (kt + 1 < 16) OSTAGE((kt + 1) & 1, kt + 1);
;             const char* sb = lds + (kt & 1) * 28672; const char* sa = sb + 16384;
; #pragma unroll
;             for (int ks = 0; ks < 2; ++ks) {
;                 bf16x8 fw[4], fx[3];
; #pragma unroll
;                 for (int ct = 0; ct < 4; ++ct) fw[ct] = *(const bf16x8*)(sb + swz(wn * 64 + ct * 16 + q, 4 * ks + g));
; #pragma unroll
;                 for (int tt = 0; tt < 3; ++tt) fx[tt] = *(const bf16x8*)(sa + swz(wm * 48 + tt * 16 + q, 4 * ks + g));
; #pragma unroll
;                 for (int ct = 0; ct < 4; ++ct)
; #pragma unroll
;                     for (int tt = 0; tt < 3; ++tt) acc[ct][tt] = __builtin_amdgcn_mfma_f32_16x16x32_bf16(fw[ct], fx[tt], acc[ct][tt], 0, 0, 0);
;             }
;             __syncthreads();
;         }
	ds_read_b128 v[102:105], v74 offset:49152
	ds_read_b128 v[106:109], v96 offset:32768
	ds_read_b128 v[110:113], v96 offset:36864
	ds_read_b128 v[114:117], v74 offset:53248
	v_mfma_f32_32x32x16_bf16 v[34:49], v[242:245], v[238:241], v[34:49]
	v_mfma_f32_32x32x16_bf16 v[18:33], v[246:249], v[238:241], v[18:33]
	v_lshl_add_u64 v[254:255], v[76:77], 0, s[68:69]
	global_load_lds_dwordx4 v[254:255], off
	v_lshl_add_u64 v[254:255], v[78:79], 0, s[68:69]
	s_mov_b32 m0, s7
	v_lshl_add_u64 v[76:77], v[76:77], 0, s[70:71]
	global_load_lds_dwordx4 v[254:255], off
	v_mfma_f32_32x32x16_bf16 v[50:65], v[242:245], v[250:253], v[50:65]
	v_lshl_add_u64 v[254:255], v[80:81], 0, s[68:69]
	s_mov_b32 m0, s38
	s_nop 0
	global_load_lds_dwordx4 v[254:255], off
	v_mfma_f32_32x32x16_bf16 v[2:17], v[246:249], v[250:253], v[2:17]
	s_waitcnt lgkmcnt(0)
	ds_read_b128 v[238:241], v95 offset:49152
	ds_read_b128 v[242:245], v97 offset:32768
	ds_read_b128 v[246:249], v97 offset:36864
	ds_read_b128 v[250:253], v95 offset:53248
	v_mfma_f32_32x32x16_bf16 v[34:49], v[106:109], v[102:105], v[34:49]
	v_lshl_add_u64 v[254:255], v[82:83], 0, s[68:69]
	s_mov_b32 m0, s39
	s_nop 0
	global_load_lds_dwordx4 v[254:255], off
	v_mfma_f32_32x32x16_bf16 v[18:33], v[110:113], v[102:105], v[18:33]
	v_lshl_add_u64 v[254:255], v[84:85], 0, s[68:69]
	s_mov_b32 m0, s50
	s_nop 0
	global_load_lds_dwordx4 v[254:255], off
	v_mfma_f32_32x32x16_bf16 v[50:65], v[106:109], v[114:117], v[50:65]
	v_mfma_f32_32x32x16_bf16 v[2:17], v[110:113], v[114:117], v[2:17]
	s_waitcnt lgkmcnt(0)
	ds_read_b128 v[102:105], v98 offset:49152
	ds_read_b128 v[106:109], v99 offset:32768
	ds_read_b128 v[110:113], v99 offset:36864
	ds_read_b128 v[114:117], v98 offset:53248
	v_mfma_f32_32x32x16_bf16 v[34:49], v[242:245], v[238:241], v[34:49]
	v_lshl_add_u64 v[254:255], v[86:87], 0, s[68:69]
	s_mov_b32 m0, s51
	s_nop 0
	global_load_lds_dwordx4 v[254:255], off
	v_mfma_f32_32x32x16_bf16 v[18:33], v[246:249], v[238:241], v[18:33]
	v_lshl_add_u64 v[254:255], v[88:89], 0, s[68:69]
	s_mov_b32 m0, s83
	s_nop 0
	global_load_lds_dwordx4 v[254:255], off
	v_mfma_f32_32x32x16_bf16 v[50:65], v[242:245], v[250:253], v[50:65]
	v_mfma_f32_32x32x16_bf16 v[2:17], v[246:249], v[250:253], v[2:17]
	s_waitcnt lgkmcnt(0)
	ds_read_b128 v[238:241], v100 offset:49152
	ds_read_b128 v[242:245], v101 offset:32768
	ds_read_b128 v[246:249], v101 offset:36864
	ds_read_b128 v[250:253], v100 offset:53248
	v_mfma_f32_32x32x16_bf16 v[34:49], v[106:109], v[102:105], v[34:49]
	v_lshl_add_u64 v[254:255], v[90:91], 0, s[68:69]
	s_mov_b32 m0, s90
	s_nop 0
	global_load_lds_dwordx4 v[254:255], off
	v_mfma_f32_32x32x16_bf16 v[18:33], v[110:113], v[102:105], v[18:33]
	v_mfma_f32_32x32x16_bf16 v[50:65], v[106:109], v[114:117], v[50:65]
	v_mfma_f32_32x32x16_bf16 v[2:17], v[110:113], v[114:117], v[2:17]
	s_mov_b32 m0, s86
	s_mov_b32 s86, 0
	s_waitcnt vmcnt(0) lgkmcnt(0)
	s_barrier
	global_load_lds_dwordx4 v[76:77], off
	v_lshl_add_u64 v[76:77], v[78:79], 0, s[70:71]
	s_mov_b32 m0, s87
	v_mfma_f32_32x32x16_bf16 v[34:49], v[242:245], v[238:241], v[34:49]
	global_load_lds_dwordx4 v[76:77], off
	v_lshl_add_u64 v[76:77], v[80:81], 0, s[70:71]
	s_mov_b32 m0, s88
	s_mov_b32 s88, 0
	global_load_lds_dwordx4 v[76:77], off
	v_lshl_add_u64 v[76:77], v[82:83], 0, s[70:71]
	s_mov_b32 m0, s89
	v_mfma_f32_32x32x16_bf16 v[18:33], v[246:249], v[238:241], v[18:33]
	global_load_lds_dwordx4 v[76:77], off
	v_lshl_add_u64 v[76:77], v[84:85], 0, s[70:71]
	s_mov_b32 m0, s91
	s_nop 0
	global_load_lds_dwordx4 v[76:77], off
	v_lshl_add_u64 v[76:77], v[86:87], 0, s[70:71]
	s_mov_b32 m0, s92
	v_mfma_f32_32x32x16_bf16 v[50:65], v[242:245], v[250:253], v[50:65]
	global_load_lds_dwordx4 v[76:77], off
	v_lshl_add_u64 v[76:77], v[88:89], 0, s[70:71]
	s_mov_b32 m0, s93
	s_nop 0
	global_load_lds_dwordx4 v[76:77], off
	v_lshl_add_u64 v[76:77], v[90:91], 0, s[70:71]
	s_mov_b32 m0, s94
	v_mfma_f32_32x32x16_bf16 v[2:17], v[246:249], v[250:253], v[2:17]
	global_load_lds_dwordx4 v[76:77], off
	ds_read_b128 v[76:79], v74 offset:16384
	ds_read_b128 v[80:83], v96
	ds_read_b128 v[84:87], v96 offset:4096
	ds_read_b128 v[88:91], v74 offset:20480
	s_waitcnt lgkmcnt(0)
	v_mfma_f32_32x32x16_bf16 v[34:49], v[80:83], v[76:79], v[34:49]
	v_mfma_f32_32x32x16_bf16 v[18:33], v[84:87], v[76:79], v[18:33]
	v_mfma_f32_32x32x16_bf16 v[50:65], v[80:83], v[88:91], v[50:65]
	v_mfma_f32_32x32x16_bf16 v[2:17], v[84:87], v[88:91], v[2:17]
	ds_read_b128 v[76:79], v95 offset:16384
	ds_read_b128 v[80:83], v97
	ds_read_b128 v[84:87], v97 offset:4096
	ds_read_b128 v[88:91], v95 offset:20480
	s_waitcnt lgkmcnt(0)
	v_mfma_f32_32x32x16_bf16 v[34:49], v[80:83], v[76:79], v[34:49]
	v_mfma_f32_32x32x16_bf16 v[18:33], v[84:87], v[76:79], v[18:33]
	v_mfma_f32_32x32x16_bf16 v[50:65], v[80:83], v[88:91], v[50:65]
	v_mfma_f32_32x32x16_bf16 v[2:17], v[84:87], v[88:91], v[2:17]
	ds_read_b128 v[76:79], v98 offset:16384
	ds_read_b128 v[80:83], v99
	ds_read_b128 v[84:87], v99 offset:4096
	ds_read_b128 v[88:91], v98 offset:20480
	s_waitcnt lgkmcnt(0)
	v_mfma_f32_32x32x16_bf16 v[34:49], v[80:83], v[76:79], v[34:49]
	v_mfma_f32_32x32x16_bf16 v[18:33], v[84:87], v[76:79], v[18:33]
	v_mfma_f32_32x32x16_bf16 v[50:65], v[80:83], v[88:91], v[50:65]
	v_mfma_f32_32x32x16_bf16 v[2:17], v[84:87], v[88:91], v[2:17]
	ds_read_b128 v[76:79], v100 offset:16384
	ds_read_b128 v[80:83], v101
	ds_read_b128 v[84:87], v101 offset:4096
	ds_read_b128 v[88:91], v100 offset:20480
	s_waitcnt vmcnt(0) lgkmcnt(0)
	s_barrier
	s_cbranch_scc1 .Lo_skipnext
	s_mov_b32 m0, s1
	s_lshr_b32 s86, s33, 3
	s_lshl_b32 s86, s86, 7
	s_and_b32 s88, s33, 7
	s_lshl_b32 s88, s88, 7
	s_ashr_i32 s87, s86, 31
	s_lshl_b64 s[92:93], s[86:87], 11
	s_add_u32 s92, s54, s92
	s_addc_u32 s93, s55, s93
	s_ashr_i32 s89, s88, 31
	s_lshl_b64 s[94:95], s[88:89], 11
	v_readlane_b32 s1, v236, 9
	s_add_u32 s94, s1, s94
	v_readlane_b32 s1, v236, 11
	s_addc_u32 s95, s1, s95
	v_lshl_add_u64 v[118:119], s[92:93], 0, v[66:67]
	global_load_lds_dwordx4 v[118:119], off
	v_lshl_add_u64 v[66:67], s[94:95], 0, v[66:67]
	s_mov_b32 m0, s7
	s_nop 0
	global_load_lds_dwordx4 v[66:67], off
	v_lshl_add_u64 v[66:67], s[92:93], 0, v[68:69]
	s_mov_b32 m0, s38
	s_nop 0
	global_load_lds_dwordx4 v[66:67], off
	v_lshl_add_u64 v[66:67], s[94:95], 0, v[68:69]
	s_mov_b32 m0, s39
	s_nop 0
	global_load_lds_dwordx4 v[66:67], off
	v_lshl_add_u64 v[66:67], s[92:93], 0, v[70:71]
	s_mov_b32 m0, s50
	s_nop 0
	global_load_lds_dwordx4 v[66:67], off
	v_lshl_add_u64 v[66:67], s[94:95], 0, v[70:71]
	s_mov_b32 m0, s51
	s_nop 0
	global_load_lds_dwordx4 v[66:67], off
	v_lshl_add_u64 v[66:67], s[92:93], 0, v[72:73]
	s_mov_b32 m0, s83
	s_nop 0
	global_load_lds_dwordx4 v[66:67], off
	v_lshl_add_u64 v[66:67], s[94:95], 0, v[72:73]
	s_mov_b32 m0, s90
	s_nop 0
	global_load_lds_dwordx4 v[66:67], off
